# RWKV scan 8 rows x 8 cols per lane (32-row items) + CU-aware two-queue mixers dispatch (chains on first WG of a CU), SSD-latent prio 3
# speedup vs baseline: 1.0918x; 1.0918x over previous
_Z6k_mega1P:
	v_writelane_b32 v246, s0, 10
	v_writelane_b32 v246, s1, 11
	s_load_dwordx2 s[98:99], s[0:1], 0x138
	s_getreg_b32 s100, hwreg(HW_REG_LDS_ALLOC, 0, 12)
	v_and_b32_e32 v242, 0x3ff, v0
	v_mov_b32_e32 v244, 0
	s_cmp_eq_u32 s100, 0
	s_cselect_b32 s100, 1, 0
	v_mov_b32_e32 v243, s100
	v_cmp_eq_u32_e32 vcc, 0, v242
	s_waitcnt lgkmcnt(0)
	s_and_saveexec_b64 s[100:101], vcc
	s_cbranch_execz .Lrole_census_skip
	global_atomic_add v244, v243, s[98:99] offset:16
.Lrole_census_skip:
	s_mov_b64 exec, s[100:101]
	s_mov_b32 s73, s2
	s_load_dwordx16 s[80:95], s[0:1], 0x140
	s_load_dword s2, s[0:1], 0x1b8
	s_load_dwordx2 s[96:97], s[0:1], 0x1b0
	s_add_u32 s10, s0, 0x1b0
	v_and_b32_e32 v226, 0x3ff, v0
	s_addc_u32 s11, s1, 0
	v_cmp_eq_u32_e64 s[74:75], 0, v226
	s_waitcnt lgkmcnt(0)
	v_writelane_b32 v241, s2, 0
	s_and_saveexec_b64 s[4:5], s[74:75]
	s_cbranch_execz .LBB0_2
	v_mov_b32_e32 v2, 0
	v_mov_b32_e32 v3, v2
	v_mov_b32_e32 v4, v2
	v_mov_b32_e32 v5, v2
	v_mov_b32_e32 v1, 0x12000
	ds_write_b128 v1, v[2:5]

.LBB0_741:
	v_writelane_b32 v240, s76, 25
	s_nop 1
	v_writelane_b32 v240, s77, 26
	v_writelane_b32 v240, s78, 27
	v_writelane_b32 v240, s79, 28
	v_writelane_b32 v240, s74, 29
	s_nop 1
	v_writelane_b32 v240, s75, 30
	v_writelane_b32 v240, s72, 31
	s_or_b64 exec, exec, s[0:1]
	v_writelane_b32 v240, s96, 32
	s_mov_b32 s0, s96
	s_waitcnt lgkmcnt(0)
	v_writelane_b32 v240, s97, 33
	s_barrier
	v_writelane_b32 v240, s73, 34
	s_add_u32 s0, s94, 0x1320
	v_writelane_b32 v240, s0, 35
	s_addc_u32 s0, s95, 0
	v_writelane_b32 v240, s0, 36
	v_readlane_b32 s0, v241, 1
	v_readlane_b32 s8, v241, 9
	v_readlane_b32 s9, v241, 10
	s_add_u32 s0, s8, 0x5e00000
	v_readlane_b32 s1, v241, 2
	v_readlane_b32 s2, v241, 3
	v_readlane_b32 s3, v241, 4
	v_readlane_b32 s4, v241, 5
	v_readlane_b32 s5, v241, 6
	v_readlane_b32 s6, v241, 7
	v_readlane_b32 s7, v241, 8
	v_readlane_b32 s10, v241, 11
	v_readlane_b32 s11, v241, 12
	v_readlane_b32 s12, v241, 13
	v_readlane_b32 s13, v241, 14
	v_readlane_b32 s14, v241, 15
	v_readlane_b32 s15, v241, 16
	v_writelane_b32 v240, s0, 37
	s_addc_u32 s0, s9, 0
	v_writelane_b32 v240, s0, 38
	v_readlane_b32 s0, v241, 41
	v_readlane_b32 s10, v241, 51
	v_readlane_b32 s11, v241, 52
	s_mov_b32 s60, s10
	s_mov_b32 s61, s11
	v_writelane_b32 v240, s60, 39
	s_mov_b32 s62, s10
	v_writelane_b32 v240, s61, 40
	v_readlane_b32 s12, v241, 53
	s_mov_b32 s63, s11
	v_writelane_b32 v240, s62, 41
	v_readlane_b32 s13, v241, 54
	s_mov_b32 s64, s12
	v_writelane_b32 v240, s63, 42
	s_mov_b32 s65, s13
	v_mbcnt_lo_u32_b32 v1, -1, 0
	v_writelane_b32 v240, s64, 43
	v_readlane_b32 s2, v241, 43
	v_readlane_b32 s3, v241, 44
	s_mov_b32 s66, s12
	v_mbcnt_hi_u32_b32 v227, -1, v1
	v_bfrev_b32_e32 v1, 0.5
	v_writelane_b32 v240, s65, 44
	s_mov_b32 s67, s13
	v_mov_b32_e32 v0, 0
	v_mov_b32_e32 v109, 0x12010
	s_movk_i32 s75, 0x104
	s_movk_i32 s33, 0x7fff
	s_movk_i32 s58, 0x1600
	s_movk_i32 s59, 0x5800
	s_mov_b32 s2, 0x2aaaaaab
	s_movk_i32 s70, 0x1520
	s_mov_b32 s71, 0xffff0000
	s_mov_b32 s3, 0x7060302
	s_movk_i32 s74, 0x81
	s_movk_i32 s96, 0xff40
	s_movk_i32 s97, 0x3c0
	v_mov_b32_e32 v111, 0x3ecc95a3
	v_mov_b32_e32 v116, 1
	v_mov_b32_e32 v117, 0x160000
	v_mov_b32_e32 v86, 1.0
	v_mov_b32_e32 v118, 0xf149f2ca
	v_mov_b32_e32 v119, 0xb700
	v_mov_b32_e32 v120, 0xffffff00
	v_mov_b32_e32 v121, 0x2380
	v_mov_b32_e32 v88, 0x3f317218
	v_mov_b32_e32 v122, 0x7f800000
	v_mov_b32_e32 v123, 0x7fc00000
	v_mov_b32_e32 v124, 0xff800000
	v_lshl_or_b32 v125, v227, 2, v1
	v_mov_b32_e32 v126, 0x100
	s_movk_i32 s72, 0xa00
	s_mov_b32 s73, 0x800000
	s_mov_b32 s77, 0
	v_writelane_b32 v240, s66, 45
	v_readlane_b32 s1, v241, 42
	v_readlane_b32 s4, v241, 45
	v_readlane_b32 s5, v241, 46
	v_readlane_b32 s6, v241, 47
	v_readlane_b32 s7, v241, 48
	v_readlane_b32 s8, v241, 49
	v_readlane_b32 s9, v241, 50
	v_readlane_b32 s14, v241, 55
	v_readlane_b32 s15, v241, 56
	v_writelane_b32 v240, s67, 46
	s_getreg_b32 s98, hwreg(HW_REG_LDS_ALLOC, 0, 12)
	v_readlane_b32 s100, v241, 15
	v_readlane_b32 s101, v241, 16
	s_cmp_lg_u32 s98, 0
	s_cselect_b32 s98, 1, 0
	s_nop 2
	s_load_dword s99, s[100:101], 0x10
	s_waitcnt lgkmcnt(0)
	s_sub_u32 s99, s99, 224
	s_cmp_le_u32 s99, 64
	s_cselect_b32 s98, s98, 0
	s_nop 0
	v_writelane_b32 v246, s98, 5
	s_branch .LBB0_744

.LBB0_744:
	v_mov_b32_e32 v1, v226
	s_nop 0
	v_cmp_eq_u32_e32 vcc, 0, v1
	s_and_saveexec_b64 s[0:1], vcc
	s_cbranch_execz .LBB0_748
	s_mov_b64 s[6:7], exec
	v_mbcnt_lo_u32_b32 v1, s6, 0
	v_mbcnt_hi_u32_b32 v1, s7, v1
	v_cmp_eq_u32_e32 vcc, 0, v1
	s_and_saveexec_b64 s[4:5], vcc
	s_cbranch_execz .LBB0_747
	s_bcnt1_i32_b64 s6, s[6:7]
	v_readlane_b32 s8, v241, 1
	v_mov_b32_e32 v2, s6
	v_readlane_b32 s22, v241, 15
	v_readlane_b32 s23, v241, 16
	v_readlane_b32 s9, v241, 2
	v_readlane_b32 s10, v241, 3
	v_readlane_b32 s11, v241, 4
	v_readlane_b32 s12, v241, 5
	v_readlane_b32 s13, v241, 6
	v_readlane_b32 s98, v246, 5
	s_nop 3
	s_bitcmp1_b32 s98, 0
	s_cbranch_scc1 .Lq0_B
.Lq0_A:
	v_mov_b32_e32 v242, 1
	global_atomic_add v242, v0, v242, s[22:23] sc0
	s_waitcnt vmcnt(0)
	v_readfirstlane_b32 s99, v242
	s_nop 3
	s_cmp_lt_u32 s99, 240
	s_cbranch_scc1 .Lq0_mapA
	s_cmp_eq_u32 s98, 2
	s_cbranch_scc1 .Lq0_none
	s_mov_b32 s98, 3
	s_nop 0
	v_writelane_b32 v246, s98, 5
.Lq0_B:
	v_mov_b32_e32 v242, 1
	global_atomic_add v242, v0, v242, s[22:23] offset:8 sc0
	s_waitcnt vmcnt(0)
	v_readfirstlane_b32 s99, v242
	s_nop 3
	s_cmp_lt_u32 s99, 0x1280
	s_cbranch_scc1 .Lq0_mapB
	s_cmp_eq_u32 s98, 3
	s_cbranch_scc1 .Lq0_none
	s_mov_b32 s98, 2
	s_nop 0
	v_writelane_b32 v246, s98, 5
	s_branch .Lq0_A
.Lq0_mapA:
	s_lshl_b32 s100, s99, 1
	s_sub_u32 s100, s100, 96
	s_add_u32 s101, s99, 0x180
	s_cmp_lt_u32 s99, 48
	s_cselect_b32 s99, s101, s100
	s_branch .Lq0_done
.Lq0_mapB:
	s_lshl_b32 s100, s99, 1
	s_add_u32 s100, s100, 0x1b0
	s_add_u32 s101, s99, 688
	s_cmp_lt_u32 s99, 256
	s_cselect_b32 s99, s100, s101
	s_branch .Lq0_done
.Lq0_none:
	s_movk_i32 s99, 0x1530
.Lq0_done:
	v_mov_b32_e32 v2, s99
	v_readlane_b32 s14, v241, 7
	v_readlane_b32 s15, v241, 8
	v_readlane_b32 s16, v241, 9
	v_readlane_b32 s17, v241, 10
	v_readlane_b32 s18, v241, 11
	v_readlane_b32 s19, v241, 12
	v_readlane_b32 s20, v241, 13
	v_readlane_b32 s21, v241, 14

.LBB0_774:
	s_andn2_b64 vcc, exec, s[0:1]
	s_cbranch_vccnz .LBB0_776
	s_setprio 3

.Lrw0_ddone:
	s_bitcmp1_b32 s17, 0
	s_cbranch_scc1 .Lrw0_f_done
	s_bfe_u32 s19, s16, 0x20001
	s_and_b32 s20, s16, 1
	s_cmp_lt_u32 s16, 32
	s_cbranch_scc0 .Lrw0_gctx
	s_lshr_b32 s21, s16, 3
	s_lshl_b32 s22, s21, 12
	s_add_u32 s22, s22, 0x1000
	s_movk_i32 s23, 0x1000
	s_branch .Lrw0_gdone

.Lrw0_gdone:
	s_sub_u32 s29, s23, 1
	s_lshr_b32 s30, s23, 1
	s_cmp_eq_u32 s18, 0
	s_cselect_b32 s25, s30, s23
	s_sub_u32 s31, s18, 1
	s_cmp_lt_u32 s31, 2
	s_cselect_b32 s24, s30, 0
	s_cmp_eq_u32 s18, 2
	s_cselect_b32 s40, 0, 1.0
	s_mov_b32 s41, s40
	s_lshl_b32 s42, s21, 1
	s_add_u32 s42, s42, 0
	s_lshl_b32 s42, s42, 1
	s_add_u32 s42, s42, s20
	s_lshl_b32 s42, s42, 2
	s_add_u32 s42, s42, s19
	v_readlane_b32 s14, v246, 10
	v_readlane_b32 s15, v246, 11
	s_nop 4
	s_load_dwordx2 s[4:5], s[14:15], 0x178
	s_load_dwordx2 s[6:7], s[14:15], 0x188
	s_load_dwordx2 s[8:9], s[14:15], 0x198
	s_load_dwordx2 s[10:11], s[14:15], 0x98
	s_load_dwordx2 s[12:13], s[14:15], 0xc8
	s_load_dwordx2 s[26:27], s[14:15], 0xd0
	v_and_b32_e32 v87, 15, v226
	v_lshrrev_b32_e32 v127, 4, v226
	v_lshlrev_b32_e32 v95, 4, v87
	v_lshrrev_b32_e32 v108, 3, v226
	v_lshlrev_b32_e32 v108, 2, v108
	v_and_b32_e32 v112, 7, v226
	v_lshlrev_b32_e32 v112, 5, v112
	v_mul_u32_u24_e32 v93, 80, v87
	v_lshlrev_b32_e32 v110, 4, v226
	v_lshlrev_b32_e32 v115, 2, v226
	v_mul_u32_u24_e32 v1, 0x180, v127
	v_lshl_add_u32 v1, v87, 3, v1
	v_lshlrev_b32_e32 v2, 8, v127
	v_add_u32_e32 v3, v2, v95
	v_lshl_add_u32 v2, v87, 3, v2
	v_lshrrev_b32_e32 v89, 3, v87
	v_and_b32_e32 v90, 7, v87
	v_lshlrev_b32_e32 v91, 7, v127
	v_lshl_add_u32 v91, v90, 4, v91
	s_lshr_b32 s98, s17, 1
	v_add_u32_e32 v91, 0x5000, v91
	v_add_u32_e32 v92, 0xa000, v110
	v_cmp_eq_u32_e32 vcc, s98, v89
	s_nop 1
	v_cndmask_b32_e32 v4, v92, v91, vcc
	v_lshlrev_b32_e32 v5, 7, v127
	v_lshl_add_u32 v5, v87, 2, v5
	s_mov_b32 s30, 0xaaaaaab
	s_lshl_b32 s31, s19, 7
	v_mul_hi_u32 v87, v226, s30
	v_mul_u32_u24_e32 v89, 24, v87
	v_sub_u32_e32 v89, v226, v89
	v_add_u32_e32 v15, -1, v87
	v_lshrrev_b32_e32 v90, 3, v89
	v_and_b32_e32 v89, 7, v89
	v_lshlrev_b32_e32 v90, 9, v90
	v_lshl_add_u32 v91, v89, 4, v90
	v_add_u32_e32 v91, s31, v91
	v_add_u32_e32 v91, 0xd20, v91
	s_add_u32 s34, s22, s29
	s_cmp_eq_u32 s20, 0
	s_cselect_b32 s34, s22, s34
	s_waitcnt lgkmcnt(0)
	s_mul_i32 s98, s34, 0x1520
	s_mul_hi_u32 s99, s34, 0x1520
	s_add_u32 s100, s4, s98
	s_addc_u32 s101, s5, s99
	s_mul_i32 s98, s34, 0xa00
	s_mul_hi_u32 s99, s34, 0xa00
	s_add_u32 s98, s6, s98
	s_addc_u32 s99, s7, s99
	v_mov_b32_e32 v92, 0
	v_mov_b32_e32 v6, s100
	v_mov_b32_e32 v7, s101
	v_add_co_u32_e32 v6, vcc, v6, v91
	s_nop 1
	v_addc_co_u32_e32 v7, vcc, 0, v7, vcc
	s_movk_i32 s36, 0x1520
	s_mul_i32 s37, s36, -1
	s_cmp_eq_u32 s20, 0
	s_cselect_b32 s34, s36, s37
	s_movk_i32 s36, 0xa00
	s_mul_i32 s37, s36, -1
	s_cselect_b32 s35, s36, s37
	v_mov_b32_e32 v12, s34
	v_add_u32_e32 v92, 0x100, v226
	v_mul_hi_u32 v87, v92, s30
	v_mul_u32_u24_e32 v89, 24, v87
	v_sub_u32_e32 v89, v92, v89
	v_add_u32_e32 v16, -1, v87
	v_lshrrev_b32_e32 v90, 3, v89
	v_and_b32_e32 v89, 7, v89
	v_lshlrev_b32_e32 v90, 9, v90
	v_lshl_add_u32 v91, v89, 4, v90
	v_add_u32_e32 v91, s31, v91
	v_add_u32_e32 v91, 0xd20, v91
	s_lshl_b32 s36, s20, 9
	s_add_u32 s36, s36, s31
	v_add_u32_e32 v92, 0xffffff50, v226
	v_lshrrev_b32_e32 v21, 4, v92
	v_and_b32_e32 v87, 15, v92
	v_lshrrev_b32_e32 v89, 3, v87
	v_and_b32_e32 v87, 7, v87
	v_lshlrev_b32_e32 v89, 10, v89
	v_lshl_add_u32 v90, v87, 4, v89
	v_add_u32_e32 v90, s36, v90
	v_cmp_gt_u32_e32 vcc, 0xb0, v226
	s_nop 1
	v_cndmask_b32_e32 v16, v21, v16, vcc
	v_cndmask_b32_e32 v91, v90, v91, vcc
	v_mov_b32_e32 v87, s35
	v_mov_b32_e32 v89, s34
	v_cndmask_b32_e32 v13, v87, v89, vcc
	v_mov_b32_e32 v87, s98
	v_mov_b32_e32 v89, s100
	v_cndmask_b32_e32 v8, v87, v89, vcc
	v_mov_b32_e32 v87, s99
	v_mov_b32_e32 v89, s101
	v_cndmask_b32_e32 v9, v87, v89, vcc
	v_add_co_u32_e32 v8, vcc, v8, v91
	s_nop 1
	v_addc_co_u32_e32 v9, vcc, 0, v9, vcc
	v_add_u32_e32 v92, 0x50, v226
	v_lshrrev_b32_e32 v17, 4, v92
	v_and_b32_e32 v87, 15, v92
	v_lshrrev_b32_e32 v89, 3, v87
	v_and_b32_e32 v87, 7, v87
	v_lshlrev_b32_e32 v89, 10, v89
	v_lshl_add_u32 v91, v87, 4, v89
	v_add_u32_e32 v91, s36, v91
	v_mov_b32_e32 v10, s98
	v_mov_b32_e32 v11, s99
	v_add_co_u32_e32 v10, vcc, v10, v91
	s_nop 1
	v_addc_co_u32_e32 v11, vcc, 0, v11, vcc
	v_mov_b32_e32 v14, s35
	s_add_u32 s30, s22, s29
	s_cmp_eq_u32 s20, 0
	s_cselect_b32 s30, s22, s30
	s_lshl_b32 s36, s19, 7
	s_lshl_b32 s37, s17, 5
	s_add_u32 s36, s36, s37
	s_cmp_eq_u32 s18, 2
	s_cbranch_scc1 .Lrw0_o_u2
	s_lshl_b32 s37, s20, 9
	s_add_u32 s36, s36, s37
	s_mul_i32 s98, s30, 0xa00
	s_mul_hi_u32 s99, s30, 0xa00
	s_add_u32 s98, s98, s36
	s_addc_u32 s99, s99, 0
	s_add_u32 s98, s8, s98
	s_addc_u32 s99, s9, s99
	s_movk_i32 s36, 0xa00
	s_mul_i32 s37, s36, -1
	s_cmp_eq_u32 s20, 0
	s_cselect_b32 s35, s36, s37
	s_branch .Lrw0_o_done

.Lrw0_o_done:
	v_and_b32_e32 v87, 15, v226
	v_lshlrev_b32_e32 v87, 1, v87
	v_mov_b32_e32 v18, s98
	v_mov_b32_e32 v19, s99
	v_add_co_u32_e32 v18, vcc, v18, v87
	s_nop 1
	v_addc_co_u32_e32 v19, vcc, 0, v19, vcc
	v_mov_b32_e32 v20, s35
	s_lshl_b32 s36, s19, 8
	s_add_u32 s98, s10, s36
	s_addc_u32 s99, s11, 0
	s_add_u32 s98, s98, 0x0
	s_addc_u32 s99, s99, 0
	global_load_dwordx4 v[70:73], v95, s[98:99]
	global_load_dwordx4 v[74:77], v95, s[98:99] offset:1024
	global_load_dwordx4 v[78:81], v95, s[98:99] offset:2048
	s_add_u32 s98, s12, s36
	s_addc_u32 s99, s13, 0
	s_add_u32 s100, s26, s36
	s_addc_u32 s101, s27, 0
	global_load_dwordx4 v[82:85], v95, s[98:99] offset:0
	global_load_dwordx4 v[96:99], v95, s[100:101] offset:0
	v_lshrrev_b32_e32 v90, 4, v95
	v_mul_u32_u24_e32 v21, 80, v90
	s_waitcnt vmcnt(0)
	ds_write_b128 v21, v[70:73] offset:46080
	ds_write_b128 v21, v[74:77] offset:46096
	ds_write_b128 v21, v[78:81] offset:46112
	ds_write_b128 v21, v[82:85] offset:46128
	ds_write_b128 v21, v[96:99] offset:46144
	v_lshrrev_b32_e32 v87, 2, v108
	v_lshl_add_u32 v87, s17, 4, v87
	v_lshl_add_u32 v89, v87, 8, v112
	v_mov_b32_e32 v22, 0
	v_mov_b32_e32 v23, 0
	v_mov_b32_e32 v24, 0
	v_mov_b32_e32 v25, 0
	v_mov_b32_e32 v26, 0
	v_mov_b32_e32 v27, 0
	v_mov_b32_e32 v28, 0
	v_mov_b32_e32 v29, 0
	s_cmp_eq_u32 s18, 0
	s_cbranch_scc0 .Lrw0_s_not0
	s_load_dwordx2 s[36:37], s[14:15], 0x28
	s_waitcnt lgkmcnt(0)
	s_lshl_b32 s98, s42, 14
	s_add_u32 s36, s36, s98
	s_addc_u32 s37, s37, 0
	global_load_dwordx4 v[22:25], v89, s[36:37]
	global_load_dwordx4 v[26:29], v89, s[36:37] offset:16
	s_branch .Lrw0_s_done
.Lrw0_s_not0:
	s_cmp_eq_u32 s18, 2
	s_cbranch_scc0 .Lrw0_s_done
	v_lshrrev_b32_e32 v90, 2, v112
	v_add_u32_e32 v91, 0, v90
	v_cmp_eq_u32_e32 vcc, v91, v87
	s_nop 1
	v_cndmask_b32_e64 v22, 0, 1.0, vcc
	v_add_u32_e32 v91, 1, v90
	v_cmp_eq_u32_e32 vcc, v91, v87
	s_nop 1
	v_cndmask_b32_e64 v23, 0, 1.0, vcc
	v_add_u32_e32 v91, 2, v90
	v_cmp_eq_u32_e32 vcc, v91, v87
	s_nop 1
	v_cndmask_b32_e64 v24, 0, 1.0, vcc
	v_add_u32_e32 v91, 3, v90
	v_cmp_eq_u32_e32 vcc, v91, v87
	s_nop 1
	v_cndmask_b32_e64 v25, 0, 1.0, vcc
	v_add_u32_e32 v91, 4, v90
	v_cmp_eq_u32_e32 vcc, v91, v87
	s_nop 1
	v_cndmask_b32_e64 v26, 0, 1.0, vcc
	v_add_u32_e32 v91, 5, v90
	v_cmp_eq_u32_e32 vcc, v91, v87
	s_nop 1
	v_cndmask_b32_e64 v27, 0, 1.0, vcc
	v_add_u32_e32 v91, 6, v90
	v_cmp_eq_u32_e32 vcc, v91, v87
	s_nop 1
	v_cndmask_b32_e64 v28, 0, 1.0, vcc
	v_add_u32_e32 v91, 7, v90
	v_cmp_eq_u32_e32 vcc, v91, v87
	s_nop 1
	v_cndmask_b32_e64 v29, 0, 1.0, vcc
.Lrw0_s_done:
	s_waitcnt lgkmcnt(0)
	s_mov_b32 s28, s24
	s_mov_b32 s30, s24
	v_add_u32_e32 v87, s30, v15
	v_med3_i32 v87, v87, 0, s29
	v_mad_i64_i32 v[104:105], vcc, v87, v12, v[6:7]
	global_load_dwordx4 v[46:49], v[104:105], off
	v_add_u32_e32 v87, s30, v16
	v_med3_i32 v87, v87, 0, s29
	v_mad_i64_i32 v[104:105], vcc, v87, v13, v[8:9]
	global_load_dwordx4 v[50:53], v[104:105], off
	v_add_u32_e32 v87, s30, v17
	v_med3_i32 v87, v87, 0, s29
	v_mad_i64_i32 v[104:105], vcc, v87, v14, v[10:11]
	global_load_dwordx4 v[54:57], v[104:105], off
	s_add_u32 s30, s24, 16
	v_add_u32_e32 v87, s30, v15
	v_med3_i32 v87, v87, 0, s29
	v_mad_i64_i32 v[104:105], vcc, v87, v12, v[6:7]
	global_load_dwordx4 v[58:61], v[104:105], off
	v_add_u32_e32 v87, s30, v16
	v_med3_i32 v87, v87, 0, s29
	v_mad_i64_i32 v[104:105], vcc, v87, v13, v[8:9]
	global_load_dwordx4 v[62:65], v[104:105], off
	v_add_u32_e32 v87, s30, v17
	v_med3_i32 v87, v87, 0, s29
	v_mad_i64_i32 v[104:105], vcc, v87, v14, v[10:11]
	global_load_dwordx4 v[66:69], v[104:105], off
	s_mov_b32 s35, 0
.Lrw0_loop:
	s_waitcnt vmcnt(0)
	ds_write_b128 v110, v[46:49] offset:26624
	ds_write_b128 v110, v[50:53] offset:30720
	ds_write_b128 v110, v[54:57] offset:34816
	s_waitcnt lgkmcnt(0)
	s_barrier
	s_add_u32 s30, s28, 32
	v_add_u32_e32 v87, s30, v15
	v_med3_i32 v87, v87, 0, s29
	v_mad_i64_i32 v[104:105], vcc, v87, v12, v[6:7]
	global_load_dwordx4 v[46:49], v[104:105], off
	v_add_u32_e32 v87, s30, v16
	v_med3_i32 v87, v87, 0, s29
	v_mad_i64_i32 v[104:105], vcc, v87, v13, v[8:9]
	global_load_dwordx4 v[50:53], v[104:105], off
	v_add_u32_e32 v87, s30, v17
	v_med3_i32 v87, v87, 0, s29
	v_mad_i64_i32 v[104:105], vcc, v87, v14, v[10:11]
	global_load_dwordx4 v[54:57], v[104:105], off
	s_cmp_eq_u32 s35, 0
	s_cbranch_scc1 .Lrw0_noout
	ds_read_b32 v89, v5 offset:24576
	ds_read_b32 v90, v5 offset:24640
	s_sub_u32 s98, s28, 16
	v_add_u32_e32 v87, s98, v127
	v_mad_i64_i32 v[104:105], vcc, v87, v20, v[18:19]
	s_waitcnt lgkmcnt(0)
	v_cvt_pk_bf16_f32 v89, v89, v90
	global_store_short v[104:105], v89, off
	global_store_short_d16_hi v[104:105], v89, off offset:32
.Lrw0_noout:
	ds_read_b128 v[30:33], v93 offset:46080
	ds_read_b128 v[34:37], v93 offset:46096
	ds_read_b128 v[38:41], v93 offset:46112
	ds_read_b128 v[42:45], v93 offset:46128
	ds_read_b64 v[70:71], v1 offset:27008
	ds_read_b64 v[72:73], v1 offset:26624
	ds_read_b64 v[74:75], v1 offset:27392
	ds_read_b64 v[76:77], v1 offset:27136
	ds_read_b64 v[78:79], v1 offset:26752
	ds_read_b64 v[80:81], v1 offset:27520
	ds_read_b64 v[82:83], v1 offset:27264
	ds_read_b64 v[84:85], v1 offset:26880
	ds_read_b64 v[96:97], v1 offset:27648
	ds_read_b64 v[128:129], v2 offset:33536
	ds_read_b64 v[130:131], v2 offset:33664
	v_add_u32_e32 v87, s28, v127
	v_cmp_ne_u32_e32 vcc, 0, v87
	s_nop 1
	v_cndmask_b32_e64 v98, 0, 0.5, vcc
	v_cmp_ne_u32_e32 vcc, s29, v87
	s_nop 1
	v_cndmask_b32_e64 v100, 0, 0.5, vcc
	s_waitcnt lgkmcnt(8)
	v_lshlrev_b32_e32 v132, 16, v70
	v_and_b32_e32 v133, 0xffff0000, v70
	v_lshlrev_b32_e32 v134, 16, v71
	v_and_b32_e32 v135, 0xffff0000, v71
	v_lshlrev_b32_e32 v136, 16, v72
	v_and_b32_e32 v137, 0xffff0000, v72
	v_lshlrev_b32_e32 v138, 16, v73
	v_and_b32_e32 v139, 0xffff0000, v73
	v_lshlrev_b32_e32 v140, 16, v74
	v_and_b32_e32 v141, 0xffff0000, v74
	v_lshlrev_b32_e32 v142, 16, v75
	v_and_b32_e32 v143, 0xffff0000, v75
	v_pk_mul_f32 v[136:137], v[136:137], v[98:99] op_sel_hi:[1,0]
	v_pk_fma_f32 v[136:137], v[140:141], v[100:101], v[136:137] op_sel_hi:[1,0,1]
	v_pk_add_f32 v[136:137], v[136:137], v[132:133] neg_lo:[0,1] neg_hi:[0,1]
	v_pk_fma_f32 v[144:145], v[30:31], v[136:137], v[132:133]
	v_pk_mul_f32 v[138:139], v[138:139], v[98:99] op_sel_hi:[1,0]
	v_pk_fma_f32 v[138:139], v[142:143], v[100:101], v[138:139] op_sel_hi:[1,0,1]
	v_pk_add_f32 v[138:139], v[138:139], v[134:135] neg_lo:[0,1] neg_hi:[0,1]
	v_pk_fma_f32 v[146:147], v[32:33], v[138:139], v[134:135]
	ds_read_b128 v[30:33], v93 offset:46144
	s_waitcnt lgkmcnt(6)
	v_lshlrev_b32_e32 v132, 16, v76
	v_and_b32_e32 v133, 0xffff0000, v76
	v_lshlrev_b32_e32 v134, 16, v77
	v_and_b32_e32 v135, 0xffff0000, v77
	v_lshlrev_b32_e32 v136, 16, v78
	v_and_b32_e32 v137, 0xffff0000, v78
	v_lshlrev_b32_e32 v138, 16, v79
	v_and_b32_e32 v139, 0xffff0000, v79
	v_lshlrev_b32_e32 v140, 16, v80
	v_and_b32_e32 v141, 0xffff0000, v80
	v_lshlrev_b32_e32 v142, 16, v81
	v_and_b32_e32 v143, 0xffff0000, v81
	v_pk_mul_f32 v[136:137], v[136:137], v[98:99] op_sel_hi:[1,0]
	v_pk_fma_f32 v[136:137], v[140:141], v[100:101], v[136:137] op_sel_hi:[1,0,1]
	v_pk_add_f32 v[136:137], v[136:137], v[132:133] neg_lo:[0,1] neg_hi:[0,1]
	v_pk_fma_f32 v[102:103], v[34:35], v[136:137], v[132:133]
	v_pk_mul_f32 v[138:139], v[138:139], v[98:99] op_sel_hi:[1,0]
	v_pk_fma_f32 v[138:139], v[142:143], v[100:101], v[138:139] op_sel_hi:[1,0,1]
	v_pk_add_f32 v[138:139], v[138:139], v[134:135] neg_lo:[0,1] neg_hi:[0,1]
	v_pk_fma_f32 v[104:105], v[36:37], v[138:139], v[134:135]
	s_waitcnt lgkmcnt(3)
	v_lshlrev_b32_e32 v132, 16, v82
	v_and_b32_e32 v133, 0xffff0000, v82
	v_lshlrev_b32_e32 v134, 16, v83
	v_and_b32_e32 v135, 0xffff0000, v83
	v_lshlrev_b32_e32 v136, 16, v84
	v_and_b32_e32 v137, 0xffff0000, v84
	v_lshlrev_b32_e32 v138, 16, v85
	v_and_b32_e32 v139, 0xffff0000, v85
	v_lshlrev_b32_e32 v140, 16, v96
	v_and_b32_e32 v141, 0xffff0000, v96
	v_lshlrev_b32_e32 v142, 16, v97
	v_and_b32_e32 v143, 0xffff0000, v97
	v_pk_mul_f32 v[136:137], v[136:137], v[98:99] op_sel_hi:[1,0]
	v_pk_fma_f32 v[136:137], v[140:141], v[100:101], v[136:137] op_sel_hi:[1,0,1]
	v_pk_add_f32 v[136:137], v[136:137], v[132:133] neg_lo:[0,1] neg_hi:[0,1]
	v_pk_fma_f32 v[148:149], v[38:39], v[136:137], v[132:133]
	v_pk_mul_f32 v[138:139], v[138:139], v[98:99] op_sel_hi:[1,0]
	v_pk_fma_f32 v[138:139], v[142:143], v[100:101], v[138:139] op_sel_hi:[1,0,1]
	v_pk_add_f32 v[138:139], v[138:139], v[134:135] neg_lo:[0,1] neg_hi:[0,1]
	v_pk_fma_f32 v[150:151], v[40:41], v[138:139], v[134:135]
	s_waitcnt lgkmcnt(0)
	v_lshlrev_b32_e32 v132, 16, v128
	v_and_b32_e32 v133, 0xffff0000, v128
	v_lshlrev_b32_e32 v134, 16, v129
	v_and_b32_e32 v135, 0xffff0000, v129
	v_lshlrev_b32_e32 v136, 16, v130
	v_and_b32_e32 v137, 0xffff0000, v130
	v_lshlrev_b32_e32 v138, 16, v131
	v_and_b32_e32 v139, 0xffff0000, v131
	s_mov_b32 s98, 0xbf60028b
	v_mul_f32_e32 v132, s98, v132
	v_mul_f32_e32 v133, s98, v133
	v_mul_f32_e32 v134, s98, v134
	v_mul_f32_e32 v135, s98, v135
	v_exp_f32_e32 v132, v132
	v_exp_f32_e32 v133, v133
	v_exp_f32_e32 v134, v134
	v_exp_f32_e32 v135, v135
	v_pk_mul_f32 v[140:141], v[102:103], v[42:43]
	v_pk_mul_f32 v[142:143], v[104:105], v[44:45]
	v_pk_mul_f32 v[106:107], v[140:141], v[140:141]
	v_pk_fma_f32 v[106:107], v[142:143], v[142:143], v[106:107]
	v_add_f32_e32 v106, v106, v107
	s_nop 1
	v_add_f32_dpp v106, v106, v106 row_ror:8 row_mask:0xf bank_mask:0xf bound_ctrl:1
	s_nop 1
	v_add_f32_dpp v106, v106, v106 row_ror:4 row_mask:0xf bank_mask:0xf bound_ctrl:1
	s_nop 1
	v_add_f32_dpp v106, v106, v106 row_ror:2 row_mask:0xf bank_mask:0xf bound_ctrl:1
	s_nop 1
	v_add_f32_dpp v106, v106, v106 row_ror:1 row_mask:0xf bank_mask:0xf bound_ctrl:1
	v_add_f32_e32 v106, 0x2b8cbccc, v106
	v_rsq_f32_e32 v106, v106
	v_pk_mul_f32 v[148:149], v[148:149], s[40:41] op_sel_hi:[1,0]
	v_pk_mul_f32 v[150:151], v[150:151], s[40:41] op_sel_hi:[1,0]
	v_pk_mul_f32 v[140:141], v[140:141], v[106:107] op_sel_hi:[1,0]
	v_pk_mul_f32 v[142:143], v[142:143], v[106:107] op_sel_hi:[1,0]
	v_pk_add_f32 v[70:71], v[136:137], -1.0 op_sel_hi:[1,0]
	v_pk_add_f32 v[72:73], v[138:139], -1.0 op_sel_hi:[1,0]
	v_pk_fma_f32 v[70:71], v[30:31], v[70:71], 1.0 op_sel_hi:[1,1,0]
	v_pk_fma_f32 v[72:73], v[32:33], v[72:73], 1.0 op_sel_hi:[1,1,0]
	v_pk_mul_f32 v[70:71], v[102:103], v[70:71]
	v_pk_mul_f32 v[72:73], v[104:105], v[72:73]
	v_pk_mul_f32 v[74:75], v[140:141], v[136:137]
	v_pk_mul_f32 v[76:77], v[142:143], v[138:139]
	ds_write_b128 v3, v[140:143] offset:0
	ds_write_b128 v3, v[132:135] offset:4096
	ds_write_b128 v3, v[74:77] offset:8192
	ds_write_b128 v3, v[70:73] offset:12288
	ds_write_b128 v3, v[144:147] offset:16384
	ds_write_b128 v4, v[148:151]
	s_waitcnt lgkmcnt(0)
	s_barrier
	ds_read_b128 v[30:33], v112 offset:0
	ds_read_b128 v[34:37], v112 offset:16
	ds_read_b128 v[78:81], v112 offset:12288
	ds_read_b128 v[82:85], v112 offset:12304
	ds_read_b32 v104, v108 offset:20480
	ds_read_b128 v[38:41], v112 offset:4096
	ds_read_b128 v[42:45], v112 offset:4112
	ds_read_b128 v[70:73], v112 offset:8192
	ds_read_b128 v[74:77], v112 offset:8208
	s_waitcnt lgkmcnt(7)
	v_pk_mul_f32 v[136:137], v[22:23], v[30:31]
	v_pk_fma_f32 v[136:137], v[24:25], v[32:33], v[136:137]
	v_pk_fma_f32 v[136:137], v[26:27], v[34:35], v[136:137]
	v_pk_fma_f32 v[136:137], v[28:29], v[36:37], v[136:137]
	ds_read_b128 v[30:33], v112 offset:256
	ds_read_b128 v[34:37], v112 offset:272
	ds_read_b128 v[96:99], v112 offset:16384
	ds_read_b128 v[100:103], v112 offset:16400
	v_add_f32_e32 v140, v136, v137
	s_waitcnt lgkmcnt(8)
	v_pk_mul_f32 v[128:129], v[78:79], v[104:105] op_sel_hi:[1,0]
	v_add_f32_dpp v140, v140, v140 row_half_mirror row_mask:0xf bank_mask:0xf
	v_pk_mul_f32 v[130:131], v[80:81], v[104:105] op_sel_hi:[1,0]
	v_pk_mul_f32 v[132:133], v[82:83], v[104:105] op_sel_hi:[1,0]
	v_pk_mul_f32 v[134:135], v[84:85], v[104:105] op_sel_hi:[1,0]
	ds_read_b128 v[78:81], v112 offset:12544
	ds_read_b128 v[82:85], v112 offset:12560
	ds_read_b32 v104, v108 offset:20608
	v_add_f32_dpp v140, v140, v140 quad_perm:[1,0,3,2] row_mask:0xf bank_mask:0xf
	s_waitcnt lgkmcnt(9)
	v_pk_fma_f32 v[128:129], v[22:23], v[38:39], v[128:129]
	v_pk_fma_f32 v[130:131], v[24:25], v[40:41], v[130:131]
	v_pk_fma_f32 v[132:133], v[26:27], v[42:43], v[132:133]
	v_add_f32_dpp v140, v140, v140 quad_perm:[2,3,0,1] row_mask:0xf bank_mask:0xf
	v_pk_fma_f32 v[134:135], v[28:29], v[44:45], v[134:135]
	ds_read_b128 v[38:41], v112 offset:4352
	ds_read_b128 v[42:45], v112 offset:4368
	s_waitcnt lgkmcnt(9)
	v_pk_fma_f32 v[22:23], v[140:141], v[70:71], v[128:129] op_sel_hi:[0,1,1] neg_lo:[1,0,0] neg_hi:[1,0,0]
	v_pk_fma_f32 v[24:25], v[140:141], v[72:73], v[130:131] op_sel_hi:[0,1,1] neg_lo:[1,0,0] neg_hi:[1,0,0]
	v_pk_fma_f32 v[26:27], v[140:141], v[74:75], v[132:133] op_sel_hi:[0,1,1] neg_lo:[1,0,0] neg_hi:[1,0,0]
	v_pk_fma_f32 v[28:29], v[140:141], v[76:77], v[134:135] op_sel_hi:[0,1,1] neg_lo:[1,0,0] neg_hi:[1,0,0]
	ds_read_b128 v[70:73], v112 offset:8448
	ds_read_b128 v[74:77], v112 offset:8464
	s_waitcnt lgkmcnt(7)
	v_pk_mul_f32 v[136:137], v[22:23], v[30:31]
	v_pk_mul_f32 v[138:139], v[22:23], v[96:97]
	v_pk_fma_f32 v[136:137], v[24:25], v[32:33], v[136:137]
	v_pk_fma_f32 v[138:139], v[24:25], v[98:99], v[138:139]
	v_pk_fma_f32 v[136:137], v[26:27], v[34:35], v[136:137]
	v_pk_fma_f32 v[138:139], v[26:27], v[100:101], v[138:139]
	v_pk_fma_f32 v[136:137], v[28:29], v[36:37], v[136:137]
	v_pk_fma_f32 v[138:139], v[28:29], v[102:103], v[138:139]
	ds_read_b128 v[30:33], v112 offset:512
	ds_read_b128 v[34:37], v112 offset:528
	ds_read_b128 v[96:99], v112 offset:16640
	ds_read_b128 v[100:103], v112 offset:16656
	v_add_f32_e32 v140, v136, v137
	v_add_f32_e32 v142, v138, v139
	s_waitcnt lgkmcnt(8)
	v_pk_mul_f32 v[128:129], v[78:79], v[104:105] op_sel_hi:[1,0]
	v_add_f32_dpp v140, v140, v140 row_half_mirror row_mask:0xf bank_mask:0xf
	v_add_f32_dpp v142, v142, v142 row_half_mirror row_mask:0xf bank_mask:0xf
	v_pk_mul_f32 v[130:131], v[80:81], v[104:105] op_sel_hi:[1,0]
	v_pk_mul_f32 v[132:133], v[82:83], v[104:105] op_sel_hi:[1,0]
	v_add_f32_dpp v140, v140, v140 quad_perm:[1,0,3,2] row_mask:0xf bank_mask:0xf
	v_add_f32_dpp v142, v142, v142 quad_perm:[1,0,3,2] row_mask:0xf bank_mask:0xf
	v_pk_mul_f32 v[134:135], v[84:85], v[104:105] op_sel_hi:[1,0]
	ds_read_b128 v[78:81], v112 offset:12800
	ds_read_b128 v[82:85], v112 offset:12816
	ds_read_b32 v104, v108 offset:20736
	s_waitcnt lgkmcnt(9)
	v_pk_fma_f32 v[128:129], v[22:23], v[38:39], v[128:129]
	v_add_f32_dpp v140, v140, v140 quad_perm:[2,3,0,1] row_mask:0xf bank_mask:0xf
	v_add_f32_dpp v142, v142, v142 quad_perm:[2,3,0,1] row_mask:0xf bank_mask:0xf
	v_pk_fma_f32 v[130:131], v[24:25], v[40:41], v[130:131]
	v_pk_fma_f32 v[132:133], v[26:27], v[42:43], v[132:133]
	v_pk_fma_f32 v[134:135], v[28:29], v[44:45], v[134:135]
	ds_read_b128 v[38:41], v112 offset:4608
	ds_read_b128 v[42:45], v112 offset:4624
	s_waitcnt lgkmcnt(9)
	v_pk_fma_f32 v[22:23], v[140:141], v[70:71], v[128:129] op_sel_hi:[0,1,1] neg_lo:[1,0,0] neg_hi:[1,0,0]
	v_pk_fma_f32 v[24:25], v[140:141], v[72:73], v[130:131] op_sel_hi:[0,1,1] neg_lo:[1,0,0] neg_hi:[1,0,0]
	v_pk_fma_f32 v[26:27], v[140:141], v[74:75], v[132:133] op_sel_hi:[0,1,1] neg_lo:[1,0,0] neg_hi:[1,0,0]
	v_pk_fma_f32 v[28:29], v[140:141], v[76:77], v[134:135] op_sel_hi:[0,1,1] neg_lo:[1,0,0] neg_hi:[1,0,0]
	ds_read_b128 v[70:73], v112 offset:8704
	ds_read_b128 v[74:77], v112 offset:8720
	ds_write_b32 v108, v142 offset:22528
	s_waitcnt lgkmcnt(8)
	v_pk_mul_f32 v[136:137], v[22:23], v[30:31]
	v_pk_mul_f32 v[138:139], v[22:23], v[96:97]
	v_pk_fma_f32 v[136:137], v[24:25], v[32:33], v[136:137]
	v_pk_fma_f32 v[138:139], v[24:25], v[98:99], v[138:139]
	v_pk_fma_f32 v[136:137], v[26:27], v[34:35], v[136:137]
	v_pk_fma_f32 v[138:139], v[26:27], v[100:101], v[138:139]
	v_pk_fma_f32 v[136:137], v[28:29], v[36:37], v[136:137]
	v_pk_fma_f32 v[138:139], v[28:29], v[102:103], v[138:139]
	ds_read_b128 v[30:33], v112 offset:768
	ds_read_b128 v[34:37], v112 offset:784
	ds_read_b128 v[96:99], v112 offset:16896
	ds_read_b128 v[100:103], v112 offset:16912
	v_add_f32_e32 v140, v136, v137
	v_add_f32_e32 v142, v138, v139
	s_waitcnt lgkmcnt(9)
	v_pk_mul_f32 v[128:129], v[78:79], v[104:105] op_sel_hi:[1,0]
	v_add_f32_dpp v140, v140, v140 row_half_mirror row_mask:0xf bank_mask:0xf
	v_add_f32_dpp v142, v142, v142 row_half_mirror row_mask:0xf bank_mask:0xf
	v_pk_mul_f32 v[130:131], v[80:81], v[104:105] op_sel_hi:[1,0]
	v_pk_mul_f32 v[132:133], v[82:83], v[104:105] op_sel_hi:[1,0]
	v_add_f32_dpp v140, v140, v140 quad_perm:[1,0,3,2] row_mask:0xf bank_mask:0xf
	v_add_f32_dpp v142, v142, v142 quad_perm:[1,0,3,2] row_mask:0xf bank_mask:0xf
	v_pk_mul_f32 v[134:135], v[84:85], v[104:105] op_sel_hi:[1,0]
	ds_read_b128 v[78:81], v112 offset:13056
	ds_read_b128 v[82:85], v112 offset:13072
	ds_read_b32 v104, v108 offset:20864
	s_waitcnt lgkmcnt(10)
	v_pk_fma_f32 v[128:129], v[22:23], v[38:39], v[128:129]
	v_add_f32_dpp v140, v140, v140 quad_perm:[2,3,0,1] row_mask:0xf bank_mask:0xf
	v_add_f32_dpp v142, v142, v142 quad_perm:[2,3,0,1] row_mask:0xf bank_mask:0xf
	v_pk_fma_f32 v[130:131], v[24:25], v[40:41], v[130:131]
	v_pk_fma_f32 v[132:133], v[26:27], v[42:43], v[132:133]
	v_pk_fma_f32 v[134:135], v[28:29], v[44:45], v[134:135]
	ds_read_b128 v[38:41], v112 offset:4864
	ds_read_b128 v[42:45], v112 offset:4880
	s_waitcnt lgkmcnt(10)
	v_pk_fma_f32 v[22:23], v[140:141], v[70:71], v[128:129] op_sel_hi:[0,1,1] neg_lo:[1,0,0] neg_hi:[1,0,0]
	v_pk_fma_f32 v[24:25], v[140:141], v[72:73], v[130:131] op_sel_hi:[0,1,1] neg_lo:[1,0,0] neg_hi:[1,0,0]
	v_pk_fma_f32 v[26:27], v[140:141], v[74:75], v[132:133] op_sel_hi:[0,1,1] neg_lo:[1,0,0] neg_hi:[1,0,0]
	v_pk_fma_f32 v[28:29], v[140:141], v[76:77], v[134:135] op_sel_hi:[0,1,1] neg_lo:[1,0,0] neg_hi:[1,0,0]
	ds_read_b128 v[70:73], v112 offset:8960
	ds_read_b128 v[74:77], v112 offset:8976
	ds_write_b32 v108, v142 offset:22656
	s_waitcnt lgkmcnt(8)
	v_pk_mul_f32 v[136:137], v[22:23], v[30:31]
	v_pk_mul_f32 v[138:139], v[22:23], v[96:97]
	v_pk_fma_f32 v[136:137], v[24:25], v[32:33], v[136:137]
	v_pk_fma_f32 v[138:139], v[24:25], v[98:99], v[138:139]
	v_pk_fma_f32 v[136:137], v[26:27], v[34:35], v[136:137]
	v_pk_fma_f32 v[138:139], v[26:27], v[100:101], v[138:139]
	v_pk_fma_f32 v[136:137], v[28:29], v[36:37], v[136:137]
	v_pk_fma_f32 v[138:139], v[28:29], v[102:103], v[138:139]
	ds_read_b128 v[30:33], v112 offset:1024
	ds_read_b128 v[34:37], v112 offset:1040
	ds_read_b128 v[96:99], v112 offset:17152
	ds_read_b128 v[100:103], v112 offset:17168
	v_add_f32_e32 v140, v136, v137
	v_add_f32_e32 v142, v138, v139
	s_waitcnt lgkmcnt(9)
	v_pk_mul_f32 v[128:129], v[78:79], v[104:105] op_sel_hi:[1,0]
	v_add_f32_dpp v140, v140, v140 row_half_mirror row_mask:0xf bank_mask:0xf
	v_add_f32_dpp v142, v142, v142 row_half_mirror row_mask:0xf bank_mask:0xf
	v_pk_mul_f32 v[130:131], v[80:81], v[104:105] op_sel_hi:[1,0]
	v_pk_mul_f32 v[132:133], v[82:83], v[104:105] op_sel_hi:[1,0]
	v_add_f32_dpp v140, v140, v140 quad_perm:[1,0,3,2] row_mask:0xf bank_mask:0xf
	v_add_f32_dpp v142, v142, v142 quad_perm:[1,0,3,2] row_mask:0xf bank_mask:0xf
	v_pk_mul_f32 v[134:135], v[84:85], v[104:105] op_sel_hi:[1,0]
	ds_read_b128 v[78:81], v112 offset:13312
	ds_read_b128 v[82:85], v112 offset:13328
	ds_read_b32 v104, v108 offset:20992
	s_waitcnt lgkmcnt(10)
	v_pk_fma_f32 v[128:129], v[22:23], v[38:39], v[128:129]
	v_add_f32_dpp v140, v140, v140 quad_perm:[2,3,0,1] row_mask:0xf bank_mask:0xf
	v_add_f32_dpp v142, v142, v142 quad_perm:[2,3,0,1] row_mask:0xf bank_mask:0xf
	v_pk_fma_f32 v[130:131], v[24:25], v[40:41], v[130:131]
	v_pk_fma_f32 v[132:133], v[26:27], v[42:43], v[132:133]
	v_pk_fma_f32 v[134:135], v[28:29], v[44:45], v[134:135]
	ds_read_b128 v[38:41], v112 offset:5120
	ds_read_b128 v[42:45], v112 offset:5136
	s_waitcnt lgkmcnt(10)
	v_pk_fma_f32 v[22:23], v[140:141], v[70:71], v[128:129] op_sel_hi:[0,1,1] neg_lo:[1,0,0] neg_hi:[1,0,0]
	v_pk_fma_f32 v[24:25], v[140:141], v[72:73], v[130:131] op_sel_hi:[0,1,1] neg_lo:[1,0,0] neg_hi:[1,0,0]
	v_pk_fma_f32 v[26:27], v[140:141], v[74:75], v[132:133] op_sel_hi:[0,1,1] neg_lo:[1,0,0] neg_hi:[1,0,0]
	v_pk_fma_f32 v[28:29], v[140:141], v[76:77], v[134:135] op_sel_hi:[0,1,1] neg_lo:[1,0,0] neg_hi:[1,0,0]
	ds_read_b128 v[70:73], v112 offset:9216
	ds_read_b128 v[74:77], v112 offset:9232
	ds_write_b32 v108, v142 offset:22784
	s_waitcnt lgkmcnt(8)
	v_pk_mul_f32 v[136:137], v[22:23], v[30:31]
	v_pk_mul_f32 v[138:139], v[22:23], v[96:97]
	v_pk_fma_f32 v[136:137], v[24:25], v[32:33], v[136:137]
	v_pk_fma_f32 v[138:139], v[24:25], v[98:99], v[138:139]
	v_pk_fma_f32 v[136:137], v[26:27], v[34:35], v[136:137]
	v_pk_fma_f32 v[138:139], v[26:27], v[100:101], v[138:139]
	v_pk_fma_f32 v[136:137], v[28:29], v[36:37], v[136:137]
	v_pk_fma_f32 v[138:139], v[28:29], v[102:103], v[138:139]
	ds_read_b128 v[30:33], v112 offset:1280
	ds_read_b128 v[34:37], v112 offset:1296
	ds_read_b128 v[96:99], v112 offset:17408
	ds_read_b128 v[100:103], v112 offset:17424
	v_add_f32_e32 v140, v136, v137
	v_add_f32_e32 v142, v138, v139
	s_waitcnt lgkmcnt(9)
	v_pk_mul_f32 v[128:129], v[78:79], v[104:105] op_sel_hi:[1,0]
	v_add_f32_dpp v140, v140, v140 row_half_mirror row_mask:0xf bank_mask:0xf
	v_add_f32_dpp v142, v142, v142 row_half_mirror row_mask:0xf bank_mask:0xf
	v_pk_mul_f32 v[130:131], v[80:81], v[104:105] op_sel_hi:[1,0]
	v_pk_mul_f32 v[132:133], v[82:83], v[104:105] op_sel_hi:[1,0]
	v_add_f32_dpp v140, v140, v140 quad_perm:[1,0,3,2] row_mask:0xf bank_mask:0xf
	v_add_f32_dpp v142, v142, v142 quad_perm:[1,0,3,2] row_mask:0xf bank_mask:0xf
	v_pk_mul_f32 v[134:135], v[84:85], v[104:105] op_sel_hi:[1,0]
	ds_read_b128 v[78:81], v112 offset:13568
	ds_read_b128 v[82:85], v112 offset:13584
	ds_read_b32 v104, v108 offset:21120
	s_waitcnt lgkmcnt(10)
	v_pk_fma_f32 v[128:129], v[22:23], v[38:39], v[128:129]
	v_add_f32_dpp v140, v140, v140 quad_perm:[2,3,0,1] row_mask:0xf bank_mask:0xf
	v_add_f32_dpp v142, v142, v142 quad_perm:[2,3,0,1] row_mask:0xf bank_mask:0xf
	v_pk_fma_f32 v[130:131], v[24:25], v[40:41], v[130:131]
	v_pk_fma_f32 v[132:133], v[26:27], v[42:43], v[132:133]
	v_pk_fma_f32 v[134:135], v[28:29], v[44:45], v[134:135]
	ds_read_b128 v[38:41], v112 offset:5376
	ds_read_b128 v[42:45], v112 offset:5392
	s_waitcnt lgkmcnt(10)
	v_pk_fma_f32 v[22:23], v[140:141], v[70:71], v[128:129] op_sel_hi:[0,1,1] neg_lo:[1,0,0] neg_hi:[1,0,0]
	v_pk_fma_f32 v[24:25], v[140:141], v[72:73], v[130:131] op_sel_hi:[0,1,1] neg_lo:[1,0,0] neg_hi:[1,0,0]
	v_pk_fma_f32 v[26:27], v[140:141], v[74:75], v[132:133] op_sel_hi:[0,1,1] neg_lo:[1,0,0] neg_hi:[1,0,0]
	v_pk_fma_f32 v[28:29], v[140:141], v[76:77], v[134:135] op_sel_hi:[0,1,1] neg_lo:[1,0,0] neg_hi:[1,0,0]
	ds_read_b128 v[70:73], v112 offset:9472
	ds_read_b128 v[74:77], v112 offset:9488
	ds_write_b32 v108, v142 offset:22912
	s_waitcnt lgkmcnt(8)
	v_pk_mul_f32 v[136:137], v[22:23], v[30:31]
	v_pk_mul_f32 v[138:139], v[22:23], v[96:97]
	v_pk_fma_f32 v[136:137], v[24:25], v[32:33], v[136:137]
	v_pk_fma_f32 v[138:139], v[24:25], v[98:99], v[138:139]
	v_pk_fma_f32 v[136:137], v[26:27], v[34:35], v[136:137]
	v_pk_fma_f32 v[138:139], v[26:27], v[100:101], v[138:139]
	v_pk_fma_f32 v[136:137], v[28:29], v[36:37], v[136:137]
	v_pk_fma_f32 v[138:139], v[28:29], v[102:103], v[138:139]
	ds_read_b128 v[30:33], v112 offset:1536
	ds_read_b128 v[34:37], v112 offset:1552
	ds_read_b128 v[96:99], v112 offset:17664
	ds_read_b128 v[100:103], v112 offset:17680
	v_add_f32_e32 v140, v136, v137
	v_add_f32_e32 v142, v138, v139
	s_waitcnt lgkmcnt(9)
	v_pk_mul_f32 v[128:129], v[78:79], v[104:105] op_sel_hi:[1,0]
	v_add_f32_dpp v140, v140, v140 row_half_mirror row_mask:0xf bank_mask:0xf
	v_add_f32_dpp v142, v142, v142 row_half_mirror row_mask:0xf bank_mask:0xf
	v_pk_mul_f32 v[130:131], v[80:81], v[104:105] op_sel_hi:[1,0]
	v_pk_mul_f32 v[132:133], v[82:83], v[104:105] op_sel_hi:[1,0]
	v_add_f32_dpp v140, v140, v140 quad_perm:[1,0,3,2] row_mask:0xf bank_mask:0xf
	v_add_f32_dpp v142, v142, v142 quad_perm:[1,0,3,2] row_mask:0xf bank_mask:0xf
	v_pk_mul_f32 v[134:135], v[84:85], v[104:105] op_sel_hi:[1,0]
	ds_read_b128 v[78:81], v112 offset:13824
	ds_read_b128 v[82:85], v112 offset:13840
	ds_read_b32 v104, v108 offset:21248
	s_waitcnt lgkmcnt(10)
	v_pk_fma_f32 v[128:129], v[22:23], v[38:39], v[128:129]
	v_add_f32_dpp v140, v140, v140 quad_perm:[2,3,0,1] row_mask:0xf bank_mask:0xf
	v_add_f32_dpp v142, v142, v142 quad_perm:[2,3,0,1] row_mask:0xf bank_mask:0xf
	v_pk_fma_f32 v[130:131], v[24:25], v[40:41], v[130:131]
	v_pk_fma_f32 v[132:133], v[26:27], v[42:43], v[132:133]
	v_pk_fma_f32 v[134:135], v[28:29], v[44:45], v[134:135]
	ds_read_b128 v[38:41], v112 offset:5632
	ds_read_b128 v[42:45], v112 offset:5648
	s_waitcnt lgkmcnt(10)
	v_pk_fma_f32 v[22:23], v[140:141], v[70:71], v[128:129] op_sel_hi:[0,1,1] neg_lo:[1,0,0] neg_hi:[1,0,0]
	v_pk_fma_f32 v[24:25], v[140:141], v[72:73], v[130:131] op_sel_hi:[0,1,1] neg_lo:[1,0,0] neg_hi:[1,0,0]
	v_pk_fma_f32 v[26:27], v[140:141], v[74:75], v[132:133] op_sel_hi:[0,1,1] neg_lo:[1,0,0] neg_hi:[1,0,0]
	v_pk_fma_f32 v[28:29], v[140:141], v[76:77], v[134:135] op_sel_hi:[0,1,1] neg_lo:[1,0,0] neg_hi:[1,0,0]
	ds_read_b128 v[70:73], v112 offset:9728
	ds_read_b128 v[74:77], v112 offset:9744
	ds_write_b32 v108, v142 offset:23040
	s_waitcnt lgkmcnt(8)
	v_pk_mul_f32 v[136:137], v[22:23], v[30:31]
	v_pk_mul_f32 v[138:139], v[22:23], v[96:97]
	v_pk_fma_f32 v[136:137], v[24:25], v[32:33], v[136:137]
	v_pk_fma_f32 v[138:139], v[24:25], v[98:99], v[138:139]
	v_pk_fma_f32 v[136:137], v[26:27], v[34:35], v[136:137]
	v_pk_fma_f32 v[138:139], v[26:27], v[100:101], v[138:139]
	v_pk_fma_f32 v[136:137], v[28:29], v[36:37], v[136:137]
	v_pk_fma_f32 v[138:139], v[28:29], v[102:103], v[138:139]
	ds_read_b128 v[30:33], v112 offset:1792
	ds_read_b128 v[34:37], v112 offset:1808
	ds_read_b128 v[96:99], v112 offset:17920
	ds_read_b128 v[100:103], v112 offset:17936
	v_add_f32_e32 v140, v136, v137
	v_add_f32_e32 v142, v138, v139
	s_waitcnt lgkmcnt(9)
	v_pk_mul_f32 v[128:129], v[78:79], v[104:105] op_sel_hi:[1,0]
	v_add_f32_dpp v140, v140, v140 row_half_mirror row_mask:0xf bank_mask:0xf
	v_add_f32_dpp v142, v142, v142 row_half_mirror row_mask:0xf bank_mask:0xf
	v_pk_mul_f32 v[130:131], v[80:81], v[104:105] op_sel_hi:[1,0]
	v_pk_mul_f32 v[132:133], v[82:83], v[104:105] op_sel_hi:[1,0]
	v_add_f32_dpp v140, v140, v140 quad_perm:[1,0,3,2] row_mask:0xf bank_mask:0xf
	v_add_f32_dpp v142, v142, v142 quad_perm:[1,0,3,2] row_mask:0xf bank_mask:0xf
	v_pk_mul_f32 v[134:135], v[84:85], v[104:105] op_sel_hi:[1,0]
	ds_read_b128 v[78:81], v112 offset:14080
	ds_read_b128 v[82:85], v112 offset:14096
	ds_read_b32 v104, v108 offset:21376
	s_waitcnt lgkmcnt(10)
	v_pk_fma_f32 v[128:129], v[22:23], v[38:39], v[128:129]
	v_add_f32_dpp v140, v140, v140 quad_perm:[2,3,0,1] row_mask:0xf bank_mask:0xf
	v_add_f32_dpp v142, v142, v142 quad_perm:[2,3,0,1] row_mask:0xf bank_mask:0xf
	v_pk_fma_f32 v[130:131], v[24:25], v[40:41], v[130:131]
	v_pk_fma_f32 v[132:133], v[26:27], v[42:43], v[132:133]
	v_pk_fma_f32 v[134:135], v[28:29], v[44:45], v[134:135]
	ds_read_b128 v[38:41], v112 offset:5888
	ds_read_b128 v[42:45], v112 offset:5904
	s_waitcnt lgkmcnt(10)
	v_pk_fma_f32 v[22:23], v[140:141], v[70:71], v[128:129] op_sel_hi:[0,1,1] neg_lo:[1,0,0] neg_hi:[1,0,0]
	v_pk_fma_f32 v[24:25], v[140:141], v[72:73], v[130:131] op_sel_hi:[0,1,1] neg_lo:[1,0,0] neg_hi:[1,0,0]
	v_pk_fma_f32 v[26:27], v[140:141], v[74:75], v[132:133] op_sel_hi:[0,1,1] neg_lo:[1,0,0] neg_hi:[1,0,0]
	v_pk_fma_f32 v[28:29], v[140:141], v[76:77], v[134:135] op_sel_hi:[0,1,1] neg_lo:[1,0,0] neg_hi:[1,0,0]
	ds_read_b128 v[70:73], v112 offset:9984
	ds_read_b128 v[74:77], v112 offset:10000
	ds_write_b32 v108, v142 offset:23168
	s_waitcnt lgkmcnt(8)
	v_pk_mul_f32 v[136:137], v[22:23], v[30:31]
	v_pk_mul_f32 v[138:139], v[22:23], v[96:97]
	v_pk_fma_f32 v[136:137], v[24:25], v[32:33], v[136:137]
	v_pk_fma_f32 v[138:139], v[24:25], v[98:99], v[138:139]
	v_pk_fma_f32 v[136:137], v[26:27], v[34:35], v[136:137]
	v_pk_fma_f32 v[138:139], v[26:27], v[100:101], v[138:139]
	v_pk_fma_f32 v[136:137], v[28:29], v[36:37], v[136:137]
	v_pk_fma_f32 v[138:139], v[28:29], v[102:103], v[138:139]
	ds_read_b128 v[30:33], v112 offset:2048
	ds_read_b128 v[34:37], v112 offset:2064
	ds_read_b128 v[96:99], v112 offset:18176
	ds_read_b128 v[100:103], v112 offset:18192
	v_add_f32_e32 v140, v136, v137
	v_add_f32_e32 v142, v138, v139
	s_waitcnt lgkmcnt(9)
	v_pk_mul_f32 v[128:129], v[78:79], v[104:105] op_sel_hi:[1,0]
	v_add_f32_dpp v140, v140, v140 row_half_mirror row_mask:0xf bank_mask:0xf
	v_add_f32_dpp v142, v142, v142 row_half_mirror row_mask:0xf bank_mask:0xf
	v_pk_mul_f32 v[130:131], v[80:81], v[104:105] op_sel_hi:[1,0]
	v_pk_mul_f32 v[132:133], v[82:83], v[104:105] op_sel_hi:[1,0]
	v_add_f32_dpp v140, v140, v140 quad_perm:[1,0,3,2] row_mask:0xf bank_mask:0xf
	v_add_f32_dpp v142, v142, v142 quad_perm:[1,0,3,2] row_mask:0xf bank_mask:0xf
	v_pk_mul_f32 v[134:135], v[84:85], v[104:105] op_sel_hi:[1,0]
	ds_read_b128 v[78:81], v112 offset:14336
	ds_read_b128 v[82:85], v112 offset:14352
	ds_read_b32 v104, v108 offset:21504
	s_waitcnt lgkmcnt(10)
	v_pk_fma_f32 v[128:129], v[22:23], v[38:39], v[128:129]
	v_add_f32_dpp v140, v140, v140 quad_perm:[2,3,0,1] row_mask:0xf bank_mask:0xf
	v_add_f32_dpp v142, v142, v142 quad_perm:[2,3,0,1] row_mask:0xf bank_mask:0xf
	v_pk_fma_f32 v[130:131], v[24:25], v[40:41], v[130:131]
	v_pk_fma_f32 v[132:133], v[26:27], v[42:43], v[132:133]
	v_pk_fma_f32 v[134:135], v[28:29], v[44:45], v[134:135]
	ds_read_b128 v[38:41], v112 offset:6144
	ds_read_b128 v[42:45], v112 offset:6160
	s_waitcnt lgkmcnt(10)
	v_pk_fma_f32 v[22:23], v[140:141], v[70:71], v[128:129] op_sel_hi:[0,1,1] neg_lo:[1,0,0] neg_hi:[1,0,0]
	v_pk_fma_f32 v[24:25], v[140:141], v[72:73], v[130:131] op_sel_hi:[0,1,1] neg_lo:[1,0,0] neg_hi:[1,0,0]
	v_pk_fma_f32 v[26:27], v[140:141], v[74:75], v[132:133] op_sel_hi:[0,1,1] neg_lo:[1,0,0] neg_hi:[1,0,0]
	v_pk_fma_f32 v[28:29], v[140:141], v[76:77], v[134:135] op_sel_hi:[0,1,1] neg_lo:[1,0,0] neg_hi:[1,0,0]
	ds_read_b128 v[70:73], v112 offset:10240
	ds_read_b128 v[74:77], v112 offset:10256
	ds_write_b32 v108, v142 offset:23296
	s_waitcnt lgkmcnt(8)
	v_pk_mul_f32 v[136:137], v[22:23], v[30:31]
	v_pk_mul_f32 v[138:139], v[22:23], v[96:97]
	v_pk_fma_f32 v[136:137], v[24:25], v[32:33], v[136:137]
	v_pk_fma_f32 v[138:139], v[24:25], v[98:99], v[138:139]
	v_pk_fma_f32 v[136:137], v[26:27], v[34:35], v[136:137]
	v_pk_fma_f32 v[138:139], v[26:27], v[100:101], v[138:139]
	v_pk_fma_f32 v[136:137], v[28:29], v[36:37], v[136:137]
	v_pk_fma_f32 v[138:139], v[28:29], v[102:103], v[138:139]
	ds_read_b128 v[30:33], v112 offset:2304
	ds_read_b128 v[34:37], v112 offset:2320
	ds_read_b128 v[96:99], v112 offset:18432
	ds_read_b128 v[100:103], v112 offset:18448
	v_add_f32_e32 v140, v136, v137
	v_add_f32_e32 v142, v138, v139
	s_waitcnt lgkmcnt(9)
	v_pk_mul_f32 v[128:129], v[78:79], v[104:105] op_sel_hi:[1,0]
	v_add_f32_dpp v140, v140, v140 row_half_mirror row_mask:0xf bank_mask:0xf
	v_add_f32_dpp v142, v142, v142 row_half_mirror row_mask:0xf bank_mask:0xf
	v_pk_mul_f32 v[130:131], v[80:81], v[104:105] op_sel_hi:[1,0]
	v_pk_mul_f32 v[132:133], v[82:83], v[104:105] op_sel_hi:[1,0]
	v_add_f32_dpp v140, v140, v140 quad_perm:[1,0,3,2] row_mask:0xf bank_mask:0xf
	v_add_f32_dpp v142, v142, v142 quad_perm:[1,0,3,2] row_mask:0xf bank_mask:0xf
	v_pk_mul_f32 v[134:135], v[84:85], v[104:105] op_sel_hi:[1,0]
	ds_read_b128 v[78:81], v112 offset:14592
	ds_read_b128 v[82:85], v112 offset:14608
	ds_read_b32 v104, v108 offset:21632
	s_waitcnt lgkmcnt(10)
	v_pk_fma_f32 v[128:129], v[22:23], v[38:39], v[128:129]
	v_add_f32_dpp v140, v140, v140 quad_perm:[2,3,0,1] row_mask:0xf bank_mask:0xf
	v_add_f32_dpp v142, v142, v142 quad_perm:[2,3,0,1] row_mask:0xf bank_mask:0xf
	v_pk_fma_f32 v[130:131], v[24:25], v[40:41], v[130:131]
	v_pk_fma_f32 v[132:133], v[26:27], v[42:43], v[132:133]
	v_pk_fma_f32 v[134:135], v[28:29], v[44:45], v[134:135]
	ds_read_b128 v[38:41], v112 offset:6400
	ds_read_b128 v[42:45], v112 offset:6416
	s_waitcnt lgkmcnt(10)
	v_pk_fma_f32 v[22:23], v[140:141], v[70:71], v[128:129] op_sel_hi:[0,1,1] neg_lo:[1,0,0] neg_hi:[1,0,0]
	v_pk_fma_f32 v[24:25], v[140:141], v[72:73], v[130:131] op_sel_hi:[0,1,1] neg_lo:[1,0,0] neg_hi:[1,0,0]
	v_pk_fma_f32 v[26:27], v[140:141], v[74:75], v[132:133] op_sel_hi:[0,1,1] neg_lo:[1,0,0] neg_hi:[1,0,0]
	v_pk_fma_f32 v[28:29], v[140:141], v[76:77], v[134:135] op_sel_hi:[0,1,1] neg_lo:[1,0,0] neg_hi:[1,0,0]
	ds_read_b128 v[70:73], v112 offset:10496
	ds_read_b128 v[74:77], v112 offset:10512
	ds_write_b32 v108, v142 offset:23424
	s_waitcnt lgkmcnt(8)
	v_pk_mul_f32 v[136:137], v[22:23], v[30:31]
	v_pk_mul_f32 v[138:139], v[22:23], v[96:97]
	v_pk_fma_f32 v[136:137], v[24:25], v[32:33], v[136:137]
	v_pk_fma_f32 v[138:139], v[24:25], v[98:99], v[138:139]
	v_pk_fma_f32 v[136:137], v[26:27], v[34:35], v[136:137]
	v_pk_fma_f32 v[138:139], v[26:27], v[100:101], v[138:139]
	v_pk_fma_f32 v[136:137], v[28:29], v[36:37], v[136:137]
	v_pk_fma_f32 v[138:139], v[28:29], v[102:103], v[138:139]
	ds_read_b128 v[30:33], v112 offset:2560
	ds_read_b128 v[34:37], v112 offset:2576
	ds_read_b128 v[96:99], v112 offset:18688
	ds_read_b128 v[100:103], v112 offset:18704
	v_add_f32_e32 v140, v136, v137
	v_add_f32_e32 v142, v138, v139
	s_waitcnt lgkmcnt(9)
	v_pk_mul_f32 v[128:129], v[78:79], v[104:105] op_sel_hi:[1,0]
	v_add_f32_dpp v140, v140, v140 row_half_mirror row_mask:0xf bank_mask:0xf
	v_add_f32_dpp v142, v142, v142 row_half_mirror row_mask:0xf bank_mask:0xf
	v_pk_mul_f32 v[130:131], v[80:81], v[104:105] op_sel_hi:[1,0]
	v_pk_mul_f32 v[132:133], v[82:83], v[104:105] op_sel_hi:[1,0]
	v_add_f32_dpp v140, v140, v140 quad_perm:[1,0,3,2] row_mask:0xf bank_mask:0xf
	v_add_f32_dpp v142, v142, v142 quad_perm:[1,0,3,2] row_mask:0xf bank_mask:0xf
	v_pk_mul_f32 v[134:135], v[84:85], v[104:105] op_sel_hi:[1,0]
	ds_read_b128 v[78:81], v112 offset:14848
	ds_read_b128 v[82:85], v112 offset:14864
	ds_read_b32 v104, v108 offset:21760
	s_waitcnt lgkmcnt(10)
	v_pk_fma_f32 v[128:129], v[22:23], v[38:39], v[128:129]
	v_add_f32_dpp v140, v140, v140 quad_perm:[2,3,0,1] row_mask:0xf bank_mask:0xf
	v_add_f32_dpp v142, v142, v142 quad_perm:[2,3,0,1] row_mask:0xf bank_mask:0xf
	v_pk_fma_f32 v[130:131], v[24:25], v[40:41], v[130:131]
	v_pk_fma_f32 v[132:133], v[26:27], v[42:43], v[132:133]
	v_pk_fma_f32 v[134:135], v[28:29], v[44:45], v[134:135]
	ds_read_b128 v[38:41], v112 offset:6656
	ds_read_b128 v[42:45], v112 offset:6672
	s_waitcnt lgkmcnt(10)
	v_pk_fma_f32 v[22:23], v[140:141], v[70:71], v[128:129] op_sel_hi:[0,1,1] neg_lo:[1,0,0] neg_hi:[1,0,0]
	v_pk_fma_f32 v[24:25], v[140:141], v[72:73], v[130:131] op_sel_hi:[0,1,1] neg_lo:[1,0,0] neg_hi:[1,0,0]
	v_pk_fma_f32 v[26:27], v[140:141], v[74:75], v[132:133] op_sel_hi:[0,1,1] neg_lo:[1,0,0] neg_hi:[1,0,0]
	v_pk_fma_f32 v[28:29], v[140:141], v[76:77], v[134:135] op_sel_hi:[0,1,1] neg_lo:[1,0,0] neg_hi:[1,0,0]
	ds_read_b128 v[70:73], v112 offset:10752
	ds_read_b128 v[74:77], v112 offset:10768
	ds_write_b32 v108, v142 offset:23552
	s_waitcnt lgkmcnt(8)
	v_pk_mul_f32 v[136:137], v[22:23], v[30:31]
	v_pk_mul_f32 v[138:139], v[22:23], v[96:97]
	v_pk_fma_f32 v[136:137], v[24:25], v[32:33], v[136:137]
	v_pk_fma_f32 v[138:139], v[24:25], v[98:99], v[138:139]
	v_pk_fma_f32 v[136:137], v[26:27], v[34:35], v[136:137]
	v_pk_fma_f32 v[138:139], v[26:27], v[100:101], v[138:139]
	v_pk_fma_f32 v[136:137], v[28:29], v[36:37], v[136:137]
	v_pk_fma_f32 v[138:139], v[28:29], v[102:103], v[138:139]
	ds_read_b128 v[30:33], v112 offset:2816
	ds_read_b128 v[34:37], v112 offset:2832
	ds_read_b128 v[96:99], v112 offset:18944
	ds_read_b128 v[100:103], v112 offset:18960
	v_add_f32_e32 v140, v136, v137
	v_add_f32_e32 v142, v138, v139
	s_waitcnt lgkmcnt(9)
	v_pk_mul_f32 v[128:129], v[78:79], v[104:105] op_sel_hi:[1,0]
	v_add_f32_dpp v140, v140, v140 row_half_mirror row_mask:0xf bank_mask:0xf
	v_add_f32_dpp v142, v142, v142 row_half_mirror row_mask:0xf bank_mask:0xf
	v_pk_mul_f32 v[130:131], v[80:81], v[104:105] op_sel_hi:[1,0]
	v_pk_mul_f32 v[132:133], v[82:83], v[104:105] op_sel_hi:[1,0]
	v_add_f32_dpp v140, v140, v140 quad_perm:[1,0,3,2] row_mask:0xf bank_mask:0xf
	v_add_f32_dpp v142, v142, v142 quad_perm:[1,0,3,2] row_mask:0xf bank_mask:0xf
	v_pk_mul_f32 v[134:135], v[84:85], v[104:105] op_sel_hi:[1,0]
	ds_read_b128 v[78:81], v112 offset:15104
	ds_read_b128 v[82:85], v112 offset:15120
	ds_read_b32 v104, v108 offset:21888
	s_waitcnt lgkmcnt(10)
	v_pk_fma_f32 v[128:129], v[22:23], v[38:39], v[128:129]
	v_add_f32_dpp v140, v140, v140 quad_perm:[2,3,0,1] row_mask:0xf bank_mask:0xf
	v_add_f32_dpp v142, v142, v142 quad_perm:[2,3,0,1] row_mask:0xf bank_mask:0xf
	v_pk_fma_f32 v[130:131], v[24:25], v[40:41], v[130:131]
	v_pk_fma_f32 v[132:133], v[26:27], v[42:43], v[132:133]
	v_pk_fma_f32 v[134:135], v[28:29], v[44:45], v[134:135]
	ds_read_b128 v[38:41], v112 offset:6912
	ds_read_b128 v[42:45], v112 offset:6928
	s_waitcnt lgkmcnt(10)
	v_pk_fma_f32 v[22:23], v[140:141], v[70:71], v[128:129] op_sel_hi:[0,1,1] neg_lo:[1,0,0] neg_hi:[1,0,0]
	v_pk_fma_f32 v[24:25], v[140:141], v[72:73], v[130:131] op_sel_hi:[0,1,1] neg_lo:[1,0,0] neg_hi:[1,0,0]
	v_pk_fma_f32 v[26:27], v[140:141], v[74:75], v[132:133] op_sel_hi:[0,1,1] neg_lo:[1,0,0] neg_hi:[1,0,0]
	v_pk_fma_f32 v[28:29], v[140:141], v[76:77], v[134:135] op_sel_hi:[0,1,1] neg_lo:[1,0,0] neg_hi:[1,0,0]
	ds_read_b128 v[70:73], v112 offset:11008
	ds_read_b128 v[74:77], v112 offset:11024
	ds_write_b32 v108, v142 offset:23680
	s_waitcnt lgkmcnt(8)
	v_pk_mul_f32 v[136:137], v[22:23], v[30:31]
	v_pk_mul_f32 v[138:139], v[22:23], v[96:97]
	v_pk_fma_f32 v[136:137], v[24:25], v[32:33], v[136:137]
	v_pk_fma_f32 v[138:139], v[24:25], v[98:99], v[138:139]
	v_pk_fma_f32 v[136:137], v[26:27], v[34:35], v[136:137]
	v_pk_fma_f32 v[138:139], v[26:27], v[100:101], v[138:139]
	v_pk_fma_f32 v[136:137], v[28:29], v[36:37], v[136:137]
	v_pk_fma_f32 v[138:139], v[28:29], v[102:103], v[138:139]
	ds_read_b128 v[30:33], v112 offset:3072
	ds_read_b128 v[34:37], v112 offset:3088
	ds_read_b128 v[96:99], v112 offset:19200
	ds_read_b128 v[100:103], v112 offset:19216
	v_add_f32_e32 v140, v136, v137
	v_add_f32_e32 v142, v138, v139
	s_waitcnt lgkmcnt(9)
	v_pk_mul_f32 v[128:129], v[78:79], v[104:105] op_sel_hi:[1,0]
	v_add_f32_dpp v140, v140, v140 row_half_mirror row_mask:0xf bank_mask:0xf
	v_add_f32_dpp v142, v142, v142 row_half_mirror row_mask:0xf bank_mask:0xf
	v_pk_mul_f32 v[130:131], v[80:81], v[104:105] op_sel_hi:[1,0]
	v_pk_mul_f32 v[132:133], v[82:83], v[104:105] op_sel_hi:[1,0]
	v_add_f32_dpp v140, v140, v140 quad_perm:[1,0,3,2] row_mask:0xf bank_mask:0xf
	v_add_f32_dpp v142, v142, v142 quad_perm:[1,0,3,2] row_mask:0xf bank_mask:0xf
	v_pk_mul_f32 v[134:135], v[84:85], v[104:105] op_sel_hi:[1,0]
	ds_read_b128 v[78:81], v112 offset:15360
	ds_read_b128 v[82:85], v112 offset:15376
	ds_read_b32 v104, v108 offset:22016
	s_waitcnt lgkmcnt(10)
	v_pk_fma_f32 v[128:129], v[22:23], v[38:39], v[128:129]
	v_add_f32_dpp v140, v140, v140 quad_perm:[2,3,0,1] row_mask:0xf bank_mask:0xf
	v_add_f32_dpp v142, v142, v142 quad_perm:[2,3,0,1] row_mask:0xf bank_mask:0xf
	v_pk_fma_f32 v[130:131], v[24:25], v[40:41], v[130:131]
	v_pk_fma_f32 v[132:133], v[26:27], v[42:43], v[132:133]
	v_pk_fma_f32 v[134:135], v[28:29], v[44:45], v[134:135]
	ds_read_b128 v[38:41], v112 offset:7168
	ds_read_b128 v[42:45], v112 offset:7184
	s_waitcnt lgkmcnt(10)
	v_pk_fma_f32 v[22:23], v[140:141], v[70:71], v[128:129] op_sel_hi:[0,1,1] neg_lo:[1,0,0] neg_hi:[1,0,0]
	v_pk_fma_f32 v[24:25], v[140:141], v[72:73], v[130:131] op_sel_hi:[0,1,1] neg_lo:[1,0,0] neg_hi:[1,0,0]
	v_pk_fma_f32 v[26:27], v[140:141], v[74:75], v[132:133] op_sel_hi:[0,1,1] neg_lo:[1,0,0] neg_hi:[1,0,0]
	v_pk_fma_f32 v[28:29], v[140:141], v[76:77], v[134:135] op_sel_hi:[0,1,1] neg_lo:[1,0,0] neg_hi:[1,0,0]
	ds_read_b128 v[70:73], v112 offset:11264
	ds_read_b128 v[74:77], v112 offset:11280
	ds_write_b32 v108, v142 offset:23808
	s_waitcnt lgkmcnt(8)
	v_pk_mul_f32 v[136:137], v[22:23], v[30:31]
	v_pk_mul_f32 v[138:139], v[22:23], v[96:97]
	v_pk_fma_f32 v[136:137], v[24:25], v[32:33], v[136:137]
	v_pk_fma_f32 v[138:139], v[24:25], v[98:99], v[138:139]
	v_pk_fma_f32 v[136:137], v[26:27], v[34:35], v[136:137]
	v_pk_fma_f32 v[138:139], v[26:27], v[100:101], v[138:139]
	v_pk_fma_f32 v[136:137], v[28:29], v[36:37], v[136:137]
	v_pk_fma_f32 v[138:139], v[28:29], v[102:103], v[138:139]
	ds_read_b128 v[30:33], v112 offset:3328
	ds_read_b128 v[34:37], v112 offset:3344
	ds_read_b128 v[96:99], v112 offset:19456
	ds_read_b128 v[100:103], v112 offset:19472
	v_add_f32_e32 v140, v136, v137
	v_add_f32_e32 v142, v138, v139
	s_waitcnt lgkmcnt(9)
	v_pk_mul_f32 v[128:129], v[78:79], v[104:105] op_sel_hi:[1,0]
	v_add_f32_dpp v140, v140, v140 row_half_mirror row_mask:0xf bank_mask:0xf
	v_add_f32_dpp v142, v142, v142 row_half_mirror row_mask:0xf bank_mask:0xf
	v_pk_mul_f32 v[130:131], v[80:81], v[104:105] op_sel_hi:[1,0]
	v_pk_mul_f32 v[132:133], v[82:83], v[104:105] op_sel_hi:[1,0]
	v_add_f32_dpp v140, v140, v140 quad_perm:[1,0,3,2] row_mask:0xf bank_mask:0xf
	v_add_f32_dpp v142, v142, v142 quad_perm:[1,0,3,2] row_mask:0xf bank_mask:0xf
	v_pk_mul_f32 v[134:135], v[84:85], v[104:105] op_sel_hi:[1,0]
	ds_read_b128 v[78:81], v112 offset:15616
	ds_read_b128 v[82:85], v112 offset:15632
	ds_read_b32 v104, v108 offset:22144
	s_waitcnt lgkmcnt(10)
	v_pk_fma_f32 v[128:129], v[22:23], v[38:39], v[128:129]
	v_add_f32_dpp v140, v140, v140 quad_perm:[2,3,0,1] row_mask:0xf bank_mask:0xf
	v_add_f32_dpp v142, v142, v142 quad_perm:[2,3,0,1] row_mask:0xf bank_mask:0xf
	v_pk_fma_f32 v[130:131], v[24:25], v[40:41], v[130:131]
	v_pk_fma_f32 v[132:133], v[26:27], v[42:43], v[132:133]
	v_pk_fma_f32 v[134:135], v[28:29], v[44:45], v[134:135]
	ds_read_b128 v[38:41], v112 offset:7424
	ds_read_b128 v[42:45], v112 offset:7440
	s_waitcnt lgkmcnt(10)
	v_pk_fma_f32 v[22:23], v[140:141], v[70:71], v[128:129] op_sel_hi:[0,1,1] neg_lo:[1,0,0] neg_hi:[1,0,0]
	v_pk_fma_f32 v[24:25], v[140:141], v[72:73], v[130:131] op_sel_hi:[0,1,1] neg_lo:[1,0,0] neg_hi:[1,0,0]
	v_pk_fma_f32 v[26:27], v[140:141], v[74:75], v[132:133] op_sel_hi:[0,1,1] neg_lo:[1,0,0] neg_hi:[1,0,0]
	v_pk_fma_f32 v[28:29], v[140:141], v[76:77], v[134:135] op_sel_hi:[0,1,1] neg_lo:[1,0,0] neg_hi:[1,0,0]
	ds_read_b128 v[70:73], v112 offset:11520
	ds_read_b128 v[74:77], v112 offset:11536
	ds_write_b32 v108, v142 offset:23936
	s_waitcnt lgkmcnt(8)
	v_pk_mul_f32 v[136:137], v[22:23], v[30:31]
	v_pk_mul_f32 v[138:139], v[22:23], v[96:97]
	v_pk_fma_f32 v[136:137], v[24:25], v[32:33], v[136:137]
	v_pk_fma_f32 v[138:139], v[24:25], v[98:99], v[138:139]
	v_pk_fma_f32 v[136:137], v[26:27], v[34:35], v[136:137]
	v_pk_fma_f32 v[138:139], v[26:27], v[100:101], v[138:139]
	v_pk_fma_f32 v[136:137], v[28:29], v[36:37], v[136:137]
	v_pk_fma_f32 v[138:139], v[28:29], v[102:103], v[138:139]
	ds_read_b128 v[30:33], v112 offset:3584
	ds_read_b128 v[34:37], v112 offset:3600
	ds_read_b128 v[96:99], v112 offset:19712
	ds_read_b128 v[100:103], v112 offset:19728
	v_add_f32_e32 v140, v136, v137
	v_add_f32_e32 v142, v138, v139
	s_waitcnt lgkmcnt(9)
	v_pk_mul_f32 v[128:129], v[78:79], v[104:105] op_sel_hi:[1,0]
	v_add_f32_dpp v140, v140, v140 row_half_mirror row_mask:0xf bank_mask:0xf
	v_add_f32_dpp v142, v142, v142 row_half_mirror row_mask:0xf bank_mask:0xf
	v_pk_mul_f32 v[130:131], v[80:81], v[104:105] op_sel_hi:[1,0]
	v_pk_mul_f32 v[132:133], v[82:83], v[104:105] op_sel_hi:[1,0]
	v_add_f32_dpp v140, v140, v140 quad_perm:[1,0,3,2] row_mask:0xf bank_mask:0xf
	v_add_f32_dpp v142, v142, v142 quad_perm:[1,0,3,2] row_mask:0xf bank_mask:0xf
	v_pk_mul_f32 v[134:135], v[84:85], v[104:105] op_sel_hi:[1,0]
	ds_read_b128 v[78:81], v112 offset:15872
	ds_read_b128 v[82:85], v112 offset:15888
	ds_read_b32 v104, v108 offset:22272
	s_waitcnt lgkmcnt(10)
	v_pk_fma_f32 v[128:129], v[22:23], v[38:39], v[128:129]
	v_add_f32_dpp v140, v140, v140 quad_perm:[2,3,0,1] row_mask:0xf bank_mask:0xf
	v_add_f32_dpp v142, v142, v142 quad_perm:[2,3,0,1] row_mask:0xf bank_mask:0xf
	v_pk_fma_f32 v[130:131], v[24:25], v[40:41], v[130:131]
	v_pk_fma_f32 v[132:133], v[26:27], v[42:43], v[132:133]
	v_pk_fma_f32 v[134:135], v[28:29], v[44:45], v[134:135]
	ds_read_b128 v[38:41], v112 offset:7680
	ds_read_b128 v[42:45], v112 offset:7696
	s_waitcnt lgkmcnt(10)
	v_pk_fma_f32 v[22:23], v[140:141], v[70:71], v[128:129] op_sel_hi:[0,1,1] neg_lo:[1,0,0] neg_hi:[1,0,0]
	v_pk_fma_f32 v[24:25], v[140:141], v[72:73], v[130:131] op_sel_hi:[0,1,1] neg_lo:[1,0,0] neg_hi:[1,0,0]
	v_pk_fma_f32 v[26:27], v[140:141], v[74:75], v[132:133] op_sel_hi:[0,1,1] neg_lo:[1,0,0] neg_hi:[1,0,0]
	v_pk_fma_f32 v[28:29], v[140:141], v[76:77], v[134:135] op_sel_hi:[0,1,1] neg_lo:[1,0,0] neg_hi:[1,0,0]
	ds_read_b128 v[70:73], v112 offset:11776
	ds_read_b128 v[74:77], v112 offset:11792
	ds_write_b32 v108, v142 offset:24064
	s_waitcnt lgkmcnt(8)
	v_pk_mul_f32 v[136:137], v[22:23], v[30:31]
	v_pk_mul_f32 v[138:139], v[22:23], v[96:97]
	v_pk_fma_f32 v[136:137], v[24:25], v[32:33], v[136:137]
	v_pk_fma_f32 v[138:139], v[24:25], v[98:99], v[138:139]
	v_pk_fma_f32 v[136:137], v[26:27], v[34:35], v[136:137]
	v_pk_fma_f32 v[138:139], v[26:27], v[100:101], v[138:139]
	v_pk_fma_f32 v[136:137], v[28:29], v[36:37], v[136:137]
	v_pk_fma_f32 v[138:139], v[28:29], v[102:103], v[138:139]
	ds_read_b128 v[30:33], v112 offset:3840
	ds_read_b128 v[34:37], v112 offset:3856
	ds_read_b128 v[96:99], v112 offset:19968
	ds_read_b128 v[100:103], v112 offset:19984
	v_add_f32_e32 v140, v136, v137
	v_add_f32_e32 v142, v138, v139
	s_waitcnt lgkmcnt(9)
	v_pk_mul_f32 v[128:129], v[78:79], v[104:105] op_sel_hi:[1,0]
	v_add_f32_dpp v140, v140, v140 row_half_mirror row_mask:0xf bank_mask:0xf
	v_add_f32_dpp v142, v142, v142 row_half_mirror row_mask:0xf bank_mask:0xf
	v_pk_mul_f32 v[130:131], v[80:81], v[104:105] op_sel_hi:[1,0]
	v_pk_mul_f32 v[132:133], v[82:83], v[104:105] op_sel_hi:[1,0]
	v_add_f32_dpp v140, v140, v140 quad_perm:[1,0,3,2] row_mask:0xf bank_mask:0xf
	v_add_f32_dpp v142, v142, v142 quad_perm:[1,0,3,2] row_mask:0xf bank_mask:0xf
	v_pk_mul_f32 v[134:135], v[84:85], v[104:105] op_sel_hi:[1,0]
	ds_read_b128 v[78:81], v112 offset:16128
	ds_read_b128 v[82:85], v112 offset:16144
	ds_read_b32 v104, v108 offset:22400
	s_waitcnt lgkmcnt(10)
	v_pk_fma_f32 v[128:129], v[22:23], v[38:39], v[128:129]
	v_add_f32_dpp v140, v140, v140 quad_perm:[2,3,0,1] row_mask:0xf bank_mask:0xf
	v_add_f32_dpp v142, v142, v142 quad_perm:[2,3,0,1] row_mask:0xf bank_mask:0xf
	v_pk_fma_f32 v[130:131], v[24:25], v[40:41], v[130:131]
	v_pk_fma_f32 v[132:133], v[26:27], v[42:43], v[132:133]
	v_pk_fma_f32 v[134:135], v[28:29], v[44:45], v[134:135]
	ds_read_b128 v[38:41], v112 offset:7936
	ds_read_b128 v[42:45], v112 offset:7952
	s_waitcnt lgkmcnt(10)
	v_pk_fma_f32 v[22:23], v[140:141], v[70:71], v[128:129] op_sel_hi:[0,1,1] neg_lo:[1,0,0] neg_hi:[1,0,0]
	v_pk_fma_f32 v[24:25], v[140:141], v[72:73], v[130:131] op_sel_hi:[0,1,1] neg_lo:[1,0,0] neg_hi:[1,0,0]
	v_pk_fma_f32 v[26:27], v[140:141], v[74:75], v[132:133] op_sel_hi:[0,1,1] neg_lo:[1,0,0] neg_hi:[1,0,0]
	v_pk_fma_f32 v[28:29], v[140:141], v[76:77], v[134:135] op_sel_hi:[0,1,1] neg_lo:[1,0,0] neg_hi:[1,0,0]
	ds_read_b128 v[70:73], v112 offset:12032
	ds_read_b128 v[74:77], v112 offset:12048
	ds_write_b32 v108, v142 offset:24192
	s_waitcnt lgkmcnt(8)
	v_pk_mul_f32 v[136:137], v[22:23], v[30:31]
	v_pk_mul_f32 v[138:139], v[22:23], v[96:97]
	v_pk_fma_f32 v[136:137], v[24:25], v[32:33], v[136:137]
	v_pk_fma_f32 v[138:139], v[24:25], v[98:99], v[138:139]
	v_pk_fma_f32 v[136:137], v[26:27], v[34:35], v[136:137]
	v_pk_fma_f32 v[138:139], v[26:27], v[100:101], v[138:139]
	v_pk_fma_f32 v[136:137], v[28:29], v[36:37], v[136:137]
	v_pk_fma_f32 v[138:139], v[28:29], v[102:103], v[138:139]
	ds_read_b128 v[96:99], v112 offset:20224
	ds_read_b128 v[100:103], v112 offset:20240
	v_add_f32_e32 v140, v136, v137
	v_add_f32_e32 v142, v138, v139
	s_waitcnt lgkmcnt(7)
	v_pk_mul_f32 v[128:129], v[78:79], v[104:105] op_sel_hi:[1,0]
	v_add_f32_dpp v140, v140, v140 row_half_mirror row_mask:0xf bank_mask:0xf
	v_add_f32_dpp v142, v142, v142 row_half_mirror row_mask:0xf bank_mask:0xf
	v_pk_mul_f32 v[130:131], v[80:81], v[104:105] op_sel_hi:[1,0]
	v_pk_mul_f32 v[132:133], v[82:83], v[104:105] op_sel_hi:[1,0]
	v_add_f32_dpp v140, v140, v140 quad_perm:[1,0,3,2] row_mask:0xf bank_mask:0xf
	v_add_f32_dpp v142, v142, v142 quad_perm:[1,0,3,2] row_mask:0xf bank_mask:0xf
	v_pk_mul_f32 v[134:135], v[84:85], v[104:105] op_sel_hi:[1,0]
	s_waitcnt lgkmcnt(5)
	v_pk_fma_f32 v[128:129], v[22:23], v[38:39], v[128:129]
	v_add_f32_dpp v140, v140, v140 quad_perm:[2,3,0,1] row_mask:0xf bank_mask:0xf
	v_add_f32_dpp v142, v142, v142 quad_perm:[2,3,0,1] row_mask:0xf bank_mask:0xf
	v_pk_fma_f32 v[130:131], v[24:25], v[40:41], v[130:131]
	v_pk_fma_f32 v[132:133], v[26:27], v[42:43], v[132:133]
	v_pk_fma_f32 v[134:135], v[28:29], v[44:45], v[134:135]
	s_waitcnt lgkmcnt(3)
	v_pk_fma_f32 v[22:23], v[140:141], v[70:71], v[128:129] op_sel_hi:[0,1,1] neg_lo:[1,0,0] neg_hi:[1,0,0]
	v_pk_fma_f32 v[24:25], v[140:141], v[72:73], v[130:131] op_sel_hi:[0,1,1] neg_lo:[1,0,0] neg_hi:[1,0,0]
	v_pk_fma_f32 v[26:27], v[140:141], v[74:75], v[132:133] op_sel_hi:[0,1,1] neg_lo:[1,0,0] neg_hi:[1,0,0]
	v_pk_fma_f32 v[28:29], v[140:141], v[76:77], v[134:135] op_sel_hi:[0,1,1] neg_lo:[1,0,0] neg_hi:[1,0,0]
	ds_write_b32 v108, v142 offset:24320
	s_waitcnt lgkmcnt(1)
	v_pk_mul_f32 v[138:139], v[22:23], v[96:97]
	v_pk_fma_f32 v[138:139], v[24:25], v[98:99], v[138:139]
	v_pk_fma_f32 v[138:139], v[26:27], v[100:101], v[138:139]
	v_pk_fma_f32 v[138:139], v[28:29], v[102:103], v[138:139]
	v_add_f32_e32 v142, v138, v139
	s_nop 1
	v_add_f32_dpp v142, v142, v142 row_half_mirror row_mask:0xf bank_mask:0xf
	s_nop 1
	v_add_f32_dpp v142, v142, v142 quad_perm:[1,0,3,2] row_mask:0xf bank_mask:0xf
	s_nop 1
	v_add_f32_dpp v142, v142, v142 quad_perm:[2,3,0,1] row_mask:0xf bank_mask:0xf
	ds_write_b32 v108, v142 offset:24448
	s_add_u32 s28, s28, 16
	s_mov_b32 s35, 1
	s_waitcnt vmcnt(0)
	ds_write_b128 v110, v[58:61] offset:26624
	ds_write_b128 v110, v[62:65] offset:30720
	ds_write_b128 v110, v[66:69] offset:34816
	s_waitcnt lgkmcnt(0)
	s_barrier
	s_add_u32 s30, s28, 32
	v_add_u32_e32 v87, s30, v15
	v_med3_i32 v87, v87, 0, s29
	v_mad_i64_i32 v[104:105], vcc, v87, v12, v[6:7]
	global_load_dwordx4 v[58:61], v[104:105], off
	v_add_u32_e32 v87, s30, v16
	v_med3_i32 v87, v87, 0, s29
	v_mad_i64_i32 v[104:105], vcc, v87, v13, v[8:9]
	global_load_dwordx4 v[62:65], v[104:105], off
	v_add_u32_e32 v87, s30, v17
	v_med3_i32 v87, v87, 0, s29
	v_mad_i64_i32 v[104:105], vcc, v87, v14, v[10:11]
	global_load_dwordx4 v[66:69], v[104:105], off
	ds_read_b32 v89, v5 offset:22528
	ds_read_b32 v90, v5 offset:22592
	s_sub_u32 s98, s28, 16
	v_add_u32_e32 v87, s98, v127
	v_mad_i64_i32 v[104:105], vcc, v87, v20, v[18:19]
	s_waitcnt lgkmcnt(0)
	v_cvt_pk_bf16_f32 v89, v89, v90
	global_store_short v[104:105], v89, off
	global_store_short_d16_hi v[104:105], v89, off offset:32
	ds_read_b128 v[30:33], v93 offset:46080
	ds_read_b128 v[34:37], v93 offset:46096
	ds_read_b128 v[38:41], v93 offset:46112
	ds_read_b128 v[42:45], v93 offset:46128
	ds_read_b64 v[70:71], v1 offset:27008
	ds_read_b64 v[72:73], v1 offset:26624
	ds_read_b64 v[74:75], v1 offset:27392
	ds_read_b64 v[76:77], v1 offset:27136
	ds_read_b64 v[78:79], v1 offset:26752
	ds_read_b64 v[80:81], v1 offset:27520
	ds_read_b64 v[82:83], v1 offset:27264
	ds_read_b64 v[84:85], v1 offset:26880
	ds_read_b64 v[96:97], v1 offset:27648
	ds_read_b64 v[128:129], v2 offset:33536
	ds_read_b64 v[130:131], v2 offset:33664
	v_add_u32_e32 v87, s28, v127
	v_cmp_ne_u32_e32 vcc, 0, v87
	s_nop 1
	v_cndmask_b32_e64 v98, 0, 0.5, vcc
	v_cmp_ne_u32_e32 vcc, s29, v87
	s_nop 1
	v_cndmask_b32_e64 v100, 0, 0.5, vcc
	s_waitcnt lgkmcnt(8)
	v_lshlrev_b32_e32 v132, 16, v70
	v_and_b32_e32 v133, 0xffff0000, v70
	v_lshlrev_b32_e32 v134, 16, v71
	v_and_b32_e32 v135, 0xffff0000, v71
	v_lshlrev_b32_e32 v136, 16, v72
	v_and_b32_e32 v137, 0xffff0000, v72
	v_lshlrev_b32_e32 v138, 16, v73
	v_and_b32_e32 v139, 0xffff0000, v73
	v_lshlrev_b32_e32 v140, 16, v74
	v_and_b32_e32 v141, 0xffff0000, v74
	v_lshlrev_b32_e32 v142, 16, v75
	v_and_b32_e32 v143, 0xffff0000, v75
	v_pk_mul_f32 v[136:137], v[136:137], v[98:99] op_sel_hi:[1,0]
	v_pk_fma_f32 v[136:137], v[140:141], v[100:101], v[136:137] op_sel_hi:[1,0,1]
	v_pk_add_f32 v[136:137], v[136:137], v[132:133] neg_lo:[0,1] neg_hi:[0,1]
	v_pk_fma_f32 v[144:145], v[30:31], v[136:137], v[132:133]
	v_pk_mul_f32 v[138:139], v[138:139], v[98:99] op_sel_hi:[1,0]
	v_pk_fma_f32 v[138:139], v[142:143], v[100:101], v[138:139] op_sel_hi:[1,0,1]
	v_pk_add_f32 v[138:139], v[138:139], v[134:135] neg_lo:[0,1] neg_hi:[0,1]
	v_pk_fma_f32 v[146:147], v[32:33], v[138:139], v[134:135]
	ds_read_b128 v[30:33], v93 offset:46144
	s_waitcnt lgkmcnt(6)
	v_lshlrev_b32_e32 v132, 16, v76
	v_and_b32_e32 v133, 0xffff0000, v76
	v_lshlrev_b32_e32 v134, 16, v77
	v_and_b32_e32 v135, 0xffff0000, v77
	v_lshlrev_b32_e32 v136, 16, v78
	v_and_b32_e32 v137, 0xffff0000, v78
	v_lshlrev_b32_e32 v138, 16, v79
	v_and_b32_e32 v139, 0xffff0000, v79
	v_lshlrev_b32_e32 v140, 16, v80
	v_and_b32_e32 v141, 0xffff0000, v80
	v_lshlrev_b32_e32 v142, 16, v81
	v_and_b32_e32 v143, 0xffff0000, v81
	v_pk_mul_f32 v[136:137], v[136:137], v[98:99] op_sel_hi:[1,0]
	v_pk_fma_f32 v[136:137], v[140:141], v[100:101], v[136:137] op_sel_hi:[1,0,1]
	v_pk_add_f32 v[136:137], v[136:137], v[132:133] neg_lo:[0,1] neg_hi:[0,1]
	v_pk_fma_f32 v[102:103], v[34:35], v[136:137], v[132:133]
	v_pk_mul_f32 v[138:139], v[138:139], v[98:99] op_sel_hi:[1,0]
	v_pk_fma_f32 v[138:139], v[142:143], v[100:101], v[138:139] op_sel_hi:[1,0,1]
	v_pk_add_f32 v[138:139], v[138:139], v[134:135] neg_lo:[0,1] neg_hi:[0,1]
	v_pk_fma_f32 v[104:105], v[36:37], v[138:139], v[134:135]
	s_waitcnt lgkmcnt(3)
	v_lshlrev_b32_e32 v132, 16, v82
	v_and_b32_e32 v133, 0xffff0000, v82
	v_lshlrev_b32_e32 v134, 16, v83
	v_and_b32_e32 v135, 0xffff0000, v83
	v_lshlrev_b32_e32 v136, 16, v84
	v_and_b32_e32 v137, 0xffff0000, v84
	v_lshlrev_b32_e32 v138, 16, v85
	v_and_b32_e32 v139, 0xffff0000, v85
	v_lshlrev_b32_e32 v140, 16, v96
	v_and_b32_e32 v141, 0xffff0000, v96
	v_lshlrev_b32_e32 v142, 16, v97
	v_and_b32_e32 v143, 0xffff0000, v97
	v_pk_mul_f32 v[136:137], v[136:137], v[98:99] op_sel_hi:[1,0]
	v_pk_fma_f32 v[136:137], v[140:141], v[100:101], v[136:137] op_sel_hi:[1,0,1]
	v_pk_add_f32 v[136:137], v[136:137], v[132:133] neg_lo:[0,1] neg_hi:[0,1]
	v_pk_fma_f32 v[148:149], v[38:39], v[136:137], v[132:133]
	v_pk_mul_f32 v[138:139], v[138:139], v[98:99] op_sel_hi:[1,0]
	v_pk_fma_f32 v[138:139], v[142:143], v[100:101], v[138:139] op_sel_hi:[1,0,1]
	v_pk_add_f32 v[138:139], v[138:139], v[134:135] neg_lo:[0,1] neg_hi:[0,1]
	v_pk_fma_f32 v[150:151], v[40:41], v[138:139], v[134:135]
	s_waitcnt lgkmcnt(0)
	v_lshlrev_b32_e32 v132, 16, v128
	v_and_b32_e32 v133, 0xffff0000, v128
	v_lshlrev_b32_e32 v134, 16, v129
	v_and_b32_e32 v135, 0xffff0000, v129
	v_lshlrev_b32_e32 v136, 16, v130
	v_and_b32_e32 v137, 0xffff0000, v130
	v_lshlrev_b32_e32 v138, 16, v131
	v_and_b32_e32 v139, 0xffff0000, v131
	s_mov_b32 s98, 0xbf60028b
	v_mul_f32_e32 v132, s98, v132
	v_mul_f32_e32 v133, s98, v133
	v_mul_f32_e32 v134, s98, v134
	v_mul_f32_e32 v135, s98, v135
	v_exp_f32_e32 v132, v132
	v_exp_f32_e32 v133, v133
	v_exp_f32_e32 v134, v134
	v_exp_f32_e32 v135, v135
	v_pk_mul_f32 v[140:141], v[102:103], v[42:43]
	v_pk_mul_f32 v[142:143], v[104:105], v[44:45]
	v_pk_mul_f32 v[106:107], v[140:141], v[140:141]
	v_pk_fma_f32 v[106:107], v[142:143], v[142:143], v[106:107]
	v_add_f32_e32 v106, v106, v107
	s_nop 1
	v_add_f32_dpp v106, v106, v106 row_ror:8 row_mask:0xf bank_mask:0xf bound_ctrl:1
	s_nop 1
	v_add_f32_dpp v106, v106, v106 row_ror:4 row_mask:0xf bank_mask:0xf bound_ctrl:1
	s_nop 1
	v_add_f32_dpp v106, v106, v106 row_ror:2 row_mask:0xf bank_mask:0xf bound_ctrl:1
	s_nop 1
	v_add_f32_dpp v106, v106, v106 row_ror:1 row_mask:0xf bank_mask:0xf bound_ctrl:1
	v_add_f32_e32 v106, 0x2b8cbccc, v106
	v_rsq_f32_e32 v106, v106
	v_pk_mul_f32 v[148:149], v[148:149], s[40:41] op_sel_hi:[1,0]
	v_pk_mul_f32 v[150:151], v[150:151], s[40:41] op_sel_hi:[1,0]
	v_pk_mul_f32 v[140:141], v[140:141], v[106:107] op_sel_hi:[1,0]
	v_pk_mul_f32 v[142:143], v[142:143], v[106:107] op_sel_hi:[1,0]
	v_pk_add_f32 v[70:71], v[136:137], -1.0 op_sel_hi:[1,0]
	v_pk_add_f32 v[72:73], v[138:139], -1.0 op_sel_hi:[1,0]
	v_pk_fma_f32 v[70:71], v[30:31], v[70:71], 1.0 op_sel_hi:[1,1,0]
	v_pk_fma_f32 v[72:73], v[32:33], v[72:73], 1.0 op_sel_hi:[1,1,0]
	v_pk_mul_f32 v[70:71], v[102:103], v[70:71]
	v_pk_mul_f32 v[72:73], v[104:105], v[72:73]
	v_pk_mul_f32 v[74:75], v[140:141], v[136:137]
	v_pk_mul_f32 v[76:77], v[142:143], v[138:139]
	ds_write_b128 v3, v[140:143] offset:0
	ds_write_b128 v3, v[132:135] offset:4096
	ds_write_b128 v3, v[74:77] offset:8192
	ds_write_b128 v3, v[70:73] offset:12288
	ds_write_b128 v3, v[144:147] offset:16384
	ds_write_b128 v4, v[148:151]
	s_waitcnt lgkmcnt(0)
	s_barrier
	ds_read_b128 v[30:33], v112 offset:0
	ds_read_b128 v[34:37], v112 offset:16
	ds_read_b128 v[78:81], v112 offset:12288
	ds_read_b128 v[82:85], v112 offset:12304
	ds_read_b32 v104, v108 offset:20480
	ds_read_b128 v[38:41], v112 offset:4096
	ds_read_b128 v[42:45], v112 offset:4112
	ds_read_b128 v[70:73], v112 offset:8192
	ds_read_b128 v[74:77], v112 offset:8208
	s_waitcnt lgkmcnt(7)
	v_pk_mul_f32 v[136:137], v[22:23], v[30:31]
	v_pk_fma_f32 v[136:137], v[24:25], v[32:33], v[136:137]
	v_pk_fma_f32 v[136:137], v[26:27], v[34:35], v[136:137]
	v_pk_fma_f32 v[136:137], v[28:29], v[36:37], v[136:137]
	ds_read_b128 v[30:33], v112 offset:256
	ds_read_b128 v[34:37], v112 offset:272
	ds_read_b128 v[96:99], v112 offset:16384
	ds_read_b128 v[100:103], v112 offset:16400
	v_add_f32_e32 v140, v136, v137
	s_waitcnt lgkmcnt(8)
	v_pk_mul_f32 v[128:129], v[78:79], v[104:105] op_sel_hi:[1,0]
	v_add_f32_dpp v140, v140, v140 row_half_mirror row_mask:0xf bank_mask:0xf
	v_pk_mul_f32 v[130:131], v[80:81], v[104:105] op_sel_hi:[1,0]
	v_pk_mul_f32 v[132:133], v[82:83], v[104:105] op_sel_hi:[1,0]
	v_pk_mul_f32 v[134:135], v[84:85], v[104:105] op_sel_hi:[1,0]
	ds_read_b128 v[78:81], v112 offset:12544
	ds_read_b128 v[82:85], v112 offset:12560
	ds_read_b32 v104, v108 offset:20608
	v_add_f32_dpp v140, v140, v140 quad_perm:[1,0,3,2] row_mask:0xf bank_mask:0xf
	s_waitcnt lgkmcnt(9)
	v_pk_fma_f32 v[128:129], v[22:23], v[38:39], v[128:129]
	v_pk_fma_f32 v[130:131], v[24:25], v[40:41], v[130:131]
	v_pk_fma_f32 v[132:133], v[26:27], v[42:43], v[132:133]
	v_add_f32_dpp v140, v140, v140 quad_perm:[2,3,0,1] row_mask:0xf bank_mask:0xf
	v_pk_fma_f32 v[134:135], v[28:29], v[44:45], v[134:135]
	ds_read_b128 v[38:41], v112 offset:4352
	ds_read_b128 v[42:45], v112 offset:4368
	s_waitcnt lgkmcnt(9)
	v_pk_fma_f32 v[22:23], v[140:141], v[70:71], v[128:129] op_sel_hi:[0,1,1] neg_lo:[1,0,0] neg_hi:[1,0,0]
	v_pk_fma_f32 v[24:25], v[140:141], v[72:73], v[130:131] op_sel_hi:[0,1,1] neg_lo:[1,0,0] neg_hi:[1,0,0]
	v_pk_fma_f32 v[26:27], v[140:141], v[74:75], v[132:133] op_sel_hi:[0,1,1] neg_lo:[1,0,0] neg_hi:[1,0,0]
	v_pk_fma_f32 v[28:29], v[140:141], v[76:77], v[134:135] op_sel_hi:[0,1,1] neg_lo:[1,0,0] neg_hi:[1,0,0]
	ds_read_b128 v[70:73], v112 offset:8448
	ds_read_b128 v[74:77], v112 offset:8464
	s_waitcnt lgkmcnt(7)
	v_pk_mul_f32 v[136:137], v[22:23], v[30:31]
	v_pk_mul_f32 v[138:139], v[22:23], v[96:97]
	v_pk_fma_f32 v[136:137], v[24:25], v[32:33], v[136:137]
	v_pk_fma_f32 v[138:139], v[24:25], v[98:99], v[138:139]
	v_pk_fma_f32 v[136:137], v[26:27], v[34:35], v[136:137]
	v_pk_fma_f32 v[138:139], v[26:27], v[100:101], v[138:139]
	v_pk_fma_f32 v[136:137], v[28:29], v[36:37], v[136:137]
	v_pk_fma_f32 v[138:139], v[28:29], v[102:103], v[138:139]
	ds_read_b128 v[30:33], v112 offset:512
	ds_read_b128 v[34:37], v112 offset:528
	ds_read_b128 v[96:99], v112 offset:16640
	ds_read_b128 v[100:103], v112 offset:16656
	v_add_f32_e32 v140, v136, v137
	v_add_f32_e32 v142, v138, v139
	s_waitcnt lgkmcnt(8)
	v_pk_mul_f32 v[128:129], v[78:79], v[104:105] op_sel_hi:[1,0]
	v_add_f32_dpp v140, v140, v140 row_half_mirror row_mask:0xf bank_mask:0xf
	v_add_f32_dpp v142, v142, v142 row_half_mirror row_mask:0xf bank_mask:0xf
	v_pk_mul_f32 v[130:131], v[80:81], v[104:105] op_sel_hi:[1,0]
	v_pk_mul_f32 v[132:133], v[82:83], v[104:105] op_sel_hi:[1,0]
	v_add_f32_dpp v140, v140, v140 quad_perm:[1,0,3,2] row_mask:0xf bank_mask:0xf
	v_add_f32_dpp v142, v142, v142 quad_perm:[1,0,3,2] row_mask:0xf bank_mask:0xf
	v_pk_mul_f32 v[134:135], v[84:85], v[104:105] op_sel_hi:[1,0]
	ds_read_b128 v[78:81], v112 offset:12800
	ds_read_b128 v[82:85], v112 offset:12816
	ds_read_b32 v104, v108 offset:20736
	s_waitcnt lgkmcnt(9)
	v_pk_fma_f32 v[128:129], v[22:23], v[38:39], v[128:129]
	v_add_f32_dpp v140, v140, v140 quad_perm:[2,3,0,1] row_mask:0xf bank_mask:0xf
	v_add_f32_dpp v142, v142, v142 quad_perm:[2,3,0,1] row_mask:0xf bank_mask:0xf
	v_pk_fma_f32 v[130:131], v[24:25], v[40:41], v[130:131]
	v_pk_fma_f32 v[132:133], v[26:27], v[42:43], v[132:133]
	v_pk_fma_f32 v[134:135], v[28:29], v[44:45], v[134:135]
	ds_read_b128 v[38:41], v112 offset:4608
	ds_read_b128 v[42:45], v112 offset:4624
	s_waitcnt lgkmcnt(9)
	v_pk_fma_f32 v[22:23], v[140:141], v[70:71], v[128:129] op_sel_hi:[0,1,1] neg_lo:[1,0,0] neg_hi:[1,0,0]
	v_pk_fma_f32 v[24:25], v[140:141], v[72:73], v[130:131] op_sel_hi:[0,1,1] neg_lo:[1,0,0] neg_hi:[1,0,0]
	v_pk_fma_f32 v[26:27], v[140:141], v[74:75], v[132:133] op_sel_hi:[0,1,1] neg_lo:[1,0,0] neg_hi:[1,0,0]
	v_pk_fma_f32 v[28:29], v[140:141], v[76:77], v[134:135] op_sel_hi:[0,1,1] neg_lo:[1,0,0] neg_hi:[1,0,0]
	ds_read_b128 v[70:73], v112 offset:8704
	ds_read_b128 v[74:77], v112 offset:8720
	ds_write_b32 v108, v142 offset:24576
	s_waitcnt lgkmcnt(8)
	v_pk_mul_f32 v[136:137], v[22:23], v[30:31]
	v_pk_mul_f32 v[138:139], v[22:23], v[96:97]
	v_pk_fma_f32 v[136:137], v[24:25], v[32:33], v[136:137]
	v_pk_fma_f32 v[138:139], v[24:25], v[98:99], v[138:139]
	v_pk_fma_f32 v[136:137], v[26:27], v[34:35], v[136:137]
	v_pk_fma_f32 v[138:139], v[26:27], v[100:101], v[138:139]
	v_pk_fma_f32 v[136:137], v[28:29], v[36:37], v[136:137]
	v_pk_fma_f32 v[138:139], v[28:29], v[102:103], v[138:139]
	ds_read_b128 v[30:33], v112 offset:768
	ds_read_b128 v[34:37], v112 offset:784
	ds_read_b128 v[96:99], v112 offset:16896
	ds_read_b128 v[100:103], v112 offset:16912
	v_add_f32_e32 v140, v136, v137
	v_add_f32_e32 v142, v138, v139
	s_waitcnt lgkmcnt(9)
	v_pk_mul_f32 v[128:129], v[78:79], v[104:105] op_sel_hi:[1,0]
	v_add_f32_dpp v140, v140, v140 row_half_mirror row_mask:0xf bank_mask:0xf
	v_add_f32_dpp v142, v142, v142 row_half_mirror row_mask:0xf bank_mask:0xf
	v_pk_mul_f32 v[130:131], v[80:81], v[104:105] op_sel_hi:[1,0]
	v_pk_mul_f32 v[132:133], v[82:83], v[104:105] op_sel_hi:[1,0]
	v_add_f32_dpp v140, v140, v140 quad_perm:[1,0,3,2] row_mask:0xf bank_mask:0xf
	v_add_f32_dpp v142, v142, v142 quad_perm:[1,0,3,2] row_mask:0xf bank_mask:0xf
	v_pk_mul_f32 v[134:135], v[84:85], v[104:105] op_sel_hi:[1,0]
	ds_read_b128 v[78:81], v112 offset:13056
	ds_read_b128 v[82:85], v112 offset:13072
	ds_read_b32 v104, v108 offset:20864
	s_waitcnt lgkmcnt(10)
	v_pk_fma_f32 v[128:129], v[22:23], v[38:39], v[128:129]
	v_add_f32_dpp v140, v140, v140 quad_perm:[2,3,0,1] row_mask:0xf bank_mask:0xf
	v_add_f32_dpp v142, v142, v142 quad_perm:[2,3,0,1] row_mask:0xf bank_mask:0xf
	v_pk_fma_f32 v[130:131], v[24:25], v[40:41], v[130:131]
	v_pk_fma_f32 v[132:133], v[26:27], v[42:43], v[132:133]
	v_pk_fma_f32 v[134:135], v[28:29], v[44:45], v[134:135]
	ds_read_b128 v[38:41], v112 offset:4864
	ds_read_b128 v[42:45], v112 offset:4880
	s_waitcnt lgkmcnt(10)
	v_pk_fma_f32 v[22:23], v[140:141], v[70:71], v[128:129] op_sel_hi:[0,1,1] neg_lo:[1,0,0] neg_hi:[1,0,0]
	v_pk_fma_f32 v[24:25], v[140:141], v[72:73], v[130:131] op_sel_hi:[0,1,1] neg_lo:[1,0,0] neg_hi:[1,0,0]
	v_pk_fma_f32 v[26:27], v[140:141], v[74:75], v[132:133] op_sel_hi:[0,1,1] neg_lo:[1,0,0] neg_hi:[1,0,0]
	v_pk_fma_f32 v[28:29], v[140:141], v[76:77], v[134:135] op_sel_hi:[0,1,1] neg_lo:[1,0,0] neg_hi:[1,0,0]
	ds_read_b128 v[70:73], v112 offset:8960
	ds_read_b128 v[74:77], v112 offset:8976
	ds_write_b32 v108, v142 offset:24704
	s_waitcnt lgkmcnt(8)
	v_pk_mul_f32 v[136:137], v[22:23], v[30:31]
	v_pk_mul_f32 v[138:139], v[22:23], v[96:97]
	v_pk_fma_f32 v[136:137], v[24:25], v[32:33], v[136:137]
	v_pk_fma_f32 v[138:139], v[24:25], v[98:99], v[138:139]
	v_pk_fma_f32 v[136:137], v[26:27], v[34:35], v[136:137]
	v_pk_fma_f32 v[138:139], v[26:27], v[100:101], v[138:139]
	v_pk_fma_f32 v[136:137], v[28:29], v[36:37], v[136:137]
	v_pk_fma_f32 v[138:139], v[28:29], v[102:103], v[138:139]
	ds_read_b128 v[30:33], v112 offset:1024
	ds_read_b128 v[34:37], v112 offset:1040
	ds_read_b128 v[96:99], v112 offset:17152
	ds_read_b128 v[100:103], v112 offset:17168
	v_add_f32_e32 v140, v136, v137
	v_add_f32_e32 v142, v138, v139
	s_waitcnt lgkmcnt(9)
	v_pk_mul_f32 v[128:129], v[78:79], v[104:105] op_sel_hi:[1,0]
	v_add_f32_dpp v140, v140, v140 row_half_mirror row_mask:0xf bank_mask:0xf
	v_add_f32_dpp v142, v142, v142 row_half_mirror row_mask:0xf bank_mask:0xf
	v_pk_mul_f32 v[130:131], v[80:81], v[104:105] op_sel_hi:[1,0]
	v_pk_mul_f32 v[132:133], v[82:83], v[104:105] op_sel_hi:[1,0]
	v_add_f32_dpp v140, v140, v140 quad_perm:[1,0,3,2] row_mask:0xf bank_mask:0xf
	v_add_f32_dpp v142, v142, v142 quad_perm:[1,0,3,2] row_mask:0xf bank_mask:0xf
	v_pk_mul_f32 v[134:135], v[84:85], v[104:105] op_sel_hi:[1,0]
	ds_read_b128 v[78:81], v112 offset:13312
	ds_read_b128 v[82:85], v112 offset:13328
	ds_read_b32 v104, v108 offset:20992
	s_waitcnt lgkmcnt(10)
	v_pk_fma_f32 v[128:129], v[22:23], v[38:39], v[128:129]
	v_add_f32_dpp v140, v140, v140 quad_perm:[2,3,0,1] row_mask:0xf bank_mask:0xf
	v_add_f32_dpp v142, v142, v142 quad_perm:[2,3,0,1] row_mask:0xf bank_mask:0xf
	v_pk_fma_f32 v[130:131], v[24:25], v[40:41], v[130:131]
	v_pk_fma_f32 v[132:133], v[26:27], v[42:43], v[132:133]
	v_pk_fma_f32 v[134:135], v[28:29], v[44:45], v[134:135]
	ds_read_b128 v[38:41], v112 offset:5120
	ds_read_b128 v[42:45], v112 offset:5136
	s_waitcnt lgkmcnt(10)
	v_pk_fma_f32 v[22:23], v[140:141], v[70:71], v[128:129] op_sel_hi:[0,1,1] neg_lo:[1,0,0] neg_hi:[1,0,0]
	v_pk_fma_f32 v[24:25], v[140:141], v[72:73], v[130:131] op_sel_hi:[0,1,1] neg_lo:[1,0,0] neg_hi:[1,0,0]
	v_pk_fma_f32 v[26:27], v[140:141], v[74:75], v[132:133] op_sel_hi:[0,1,1] neg_lo:[1,0,0] neg_hi:[1,0,0]
	v_pk_fma_f32 v[28:29], v[140:141], v[76:77], v[134:135] op_sel_hi:[0,1,1] neg_lo:[1,0,0] neg_hi:[1,0,0]
	ds_read_b128 v[70:73], v112 offset:9216
	ds_read_b128 v[74:77], v112 offset:9232
	ds_write_b32 v108, v142 offset:24832
	s_waitcnt lgkmcnt(8)
	v_pk_mul_f32 v[136:137], v[22:23], v[30:31]
	v_pk_mul_f32 v[138:139], v[22:23], v[96:97]
	v_pk_fma_f32 v[136:137], v[24:25], v[32:33], v[136:137]
	v_pk_fma_f32 v[138:139], v[24:25], v[98:99], v[138:139]
	v_pk_fma_f32 v[136:137], v[26:27], v[34:35], v[136:137]
	v_pk_fma_f32 v[138:139], v[26:27], v[100:101], v[138:139]
	v_pk_fma_f32 v[136:137], v[28:29], v[36:37], v[136:137]
	v_pk_fma_f32 v[138:139], v[28:29], v[102:103], v[138:139]
	ds_read_b128 v[30:33], v112 offset:1280
	ds_read_b128 v[34:37], v112 offset:1296
	ds_read_b128 v[96:99], v112 offset:17408
	ds_read_b128 v[100:103], v112 offset:17424
	v_add_f32_e32 v140, v136, v137
	v_add_f32_e32 v142, v138, v139
	s_waitcnt lgkmcnt(9)
	v_pk_mul_f32 v[128:129], v[78:79], v[104:105] op_sel_hi:[1,0]
	v_add_f32_dpp v140, v140, v140 row_half_mirror row_mask:0xf bank_mask:0xf
	v_add_f32_dpp v142, v142, v142 row_half_mirror row_mask:0xf bank_mask:0xf
	v_pk_mul_f32 v[130:131], v[80:81], v[104:105] op_sel_hi:[1,0]
	v_pk_mul_f32 v[132:133], v[82:83], v[104:105] op_sel_hi:[1,0]
	v_add_f32_dpp v140, v140, v140 quad_perm:[1,0,3,2] row_mask:0xf bank_mask:0xf
	v_add_f32_dpp v142, v142, v142 quad_perm:[1,0,3,2] row_mask:0xf bank_mask:0xf
	v_pk_mul_f32 v[134:135], v[84:85], v[104:105] op_sel_hi:[1,0]
	ds_read_b128 v[78:81], v112 offset:13568
	ds_read_b128 v[82:85], v112 offset:13584
	ds_read_b32 v104, v108 offset:21120
	s_waitcnt lgkmcnt(10)
	v_pk_fma_f32 v[128:129], v[22:23], v[38:39], v[128:129]
	v_add_f32_dpp v140, v140, v140 quad_perm:[2,3,0,1] row_mask:0xf bank_mask:0xf
	v_add_f32_dpp v142, v142, v142 quad_perm:[2,3,0,1] row_mask:0xf bank_mask:0xf
	v_pk_fma_f32 v[130:131], v[24:25], v[40:41], v[130:131]
	v_pk_fma_f32 v[132:133], v[26:27], v[42:43], v[132:133]
	v_pk_fma_f32 v[134:135], v[28:29], v[44:45], v[134:135]
	ds_read_b128 v[38:41], v112 offset:5376
	ds_read_b128 v[42:45], v112 offset:5392
	s_waitcnt lgkmcnt(10)
	v_pk_fma_f32 v[22:23], v[140:141], v[70:71], v[128:129] op_sel_hi:[0,1,1] neg_lo:[1,0,0] neg_hi:[1,0,0]
	v_pk_fma_f32 v[24:25], v[140:141], v[72:73], v[130:131] op_sel_hi:[0,1,1] neg_lo:[1,0,0] neg_hi:[1,0,0]
	v_pk_fma_f32 v[26:27], v[140:141], v[74:75], v[132:133] op_sel_hi:[0,1,1] neg_lo:[1,0,0] neg_hi:[1,0,0]
	v_pk_fma_f32 v[28:29], v[140:141], v[76:77], v[134:135] op_sel_hi:[0,1,1] neg_lo:[1,0,0] neg_hi:[1,0,0]
	ds_read_b128 v[70:73], v112 offset:9472
	ds_read_b128 v[74:77], v112 offset:9488
	ds_write_b32 v108, v142 offset:24960
	s_waitcnt lgkmcnt(8)
	v_pk_mul_f32 v[136:137], v[22:23], v[30:31]
	v_pk_mul_f32 v[138:139], v[22:23], v[96:97]
	v_pk_fma_f32 v[136:137], v[24:25], v[32:33], v[136:137]
	v_pk_fma_f32 v[138:139], v[24:25], v[98:99], v[138:139]
	v_pk_fma_f32 v[136:137], v[26:27], v[34:35], v[136:137]
	v_pk_fma_f32 v[138:139], v[26:27], v[100:101], v[138:139]
	v_pk_fma_f32 v[136:137], v[28:29], v[36:37], v[136:137]
	v_pk_fma_f32 v[138:139], v[28:29], v[102:103], v[138:139]
	ds_read_b128 v[30:33], v112 offset:1536
	ds_read_b128 v[34:37], v112 offset:1552
	ds_read_b128 v[96:99], v112 offset:17664
	ds_read_b128 v[100:103], v112 offset:17680
	v_add_f32_e32 v140, v136, v137
	v_add_f32_e32 v142, v138, v139
	s_waitcnt lgkmcnt(9)
	v_pk_mul_f32 v[128:129], v[78:79], v[104:105] op_sel_hi:[1,0]
	v_add_f32_dpp v140, v140, v140 row_half_mirror row_mask:0xf bank_mask:0xf
	v_add_f32_dpp v142, v142, v142 row_half_mirror row_mask:0xf bank_mask:0xf
	v_pk_mul_f32 v[130:131], v[80:81], v[104:105] op_sel_hi:[1,0]
	v_pk_mul_f32 v[132:133], v[82:83], v[104:105] op_sel_hi:[1,0]
	v_add_f32_dpp v140, v140, v140 quad_perm:[1,0,3,2] row_mask:0xf bank_mask:0xf
	v_add_f32_dpp v142, v142, v142 quad_perm:[1,0,3,2] row_mask:0xf bank_mask:0xf
	v_pk_mul_f32 v[134:135], v[84:85], v[104:105] op_sel_hi:[1,0]
	ds_read_b128 v[78:81], v112 offset:13824
	ds_read_b128 v[82:85], v112 offset:13840
	ds_read_b32 v104, v108 offset:21248
	s_waitcnt lgkmcnt(10)
	v_pk_fma_f32 v[128:129], v[22:23], v[38:39], v[128:129]
	v_add_f32_dpp v140, v140, v140 quad_perm:[2,3,0,1] row_mask:0xf bank_mask:0xf
	v_add_f32_dpp v142, v142, v142 quad_perm:[2,3,0,1] row_mask:0xf bank_mask:0xf
	v_pk_fma_f32 v[130:131], v[24:25], v[40:41], v[130:131]
	v_pk_fma_f32 v[132:133], v[26:27], v[42:43], v[132:133]
	v_pk_fma_f32 v[134:135], v[28:29], v[44:45], v[134:135]
	ds_read_b128 v[38:41], v112 offset:5632
	ds_read_b128 v[42:45], v112 offset:5648
	s_waitcnt lgkmcnt(10)
	v_pk_fma_f32 v[22:23], v[140:141], v[70:71], v[128:129] op_sel_hi:[0,1,1] neg_lo:[1,0,0] neg_hi:[1,0,0]
	v_pk_fma_f32 v[24:25], v[140:141], v[72:73], v[130:131] op_sel_hi:[0,1,1] neg_lo:[1,0,0] neg_hi:[1,0,0]
	v_pk_fma_f32 v[26:27], v[140:141], v[74:75], v[132:133] op_sel_hi:[0,1,1] neg_lo:[1,0,0] neg_hi:[1,0,0]
	v_pk_fma_f32 v[28:29], v[140:141], v[76:77], v[134:135] op_sel_hi:[0,1,1] neg_lo:[1,0,0] neg_hi:[1,0,0]
	ds_read_b128 v[70:73], v112 offset:9728
	ds_read_b128 v[74:77], v112 offset:9744
	ds_write_b32 v108, v142 offset:25088
	s_waitcnt lgkmcnt(8)
	v_pk_mul_f32 v[136:137], v[22:23], v[30:31]
	v_pk_mul_f32 v[138:139], v[22:23], v[96:97]
	v_pk_fma_f32 v[136:137], v[24:25], v[32:33], v[136:137]
	v_pk_fma_f32 v[138:139], v[24:25], v[98:99], v[138:139]
	v_pk_fma_f32 v[136:137], v[26:27], v[34:35], v[136:137]
	v_pk_fma_f32 v[138:139], v[26:27], v[100:101], v[138:139]
	v_pk_fma_f32 v[136:137], v[28:29], v[36:37], v[136:137]
	v_pk_fma_f32 v[138:139], v[28:29], v[102:103], v[138:139]
	ds_read_b128 v[30:33], v112 offset:1792
	ds_read_b128 v[34:37], v112 offset:1808
	ds_read_b128 v[96:99], v112 offset:17920
	ds_read_b128 v[100:103], v112 offset:17936
	v_add_f32_e32 v140, v136, v137
	v_add_f32_e32 v142, v138, v139
	s_waitcnt lgkmcnt(9)
	v_pk_mul_f32 v[128:129], v[78:79], v[104:105] op_sel_hi:[1,0]
	v_add_f32_dpp v140, v140, v140 row_half_mirror row_mask:0xf bank_mask:0xf
	v_add_f32_dpp v142, v142, v142 row_half_mirror row_mask:0xf bank_mask:0xf
	v_pk_mul_f32 v[130:131], v[80:81], v[104:105] op_sel_hi:[1,0]
	v_pk_mul_f32 v[132:133], v[82:83], v[104:105] op_sel_hi:[1,0]
	v_add_f32_dpp v140, v140, v140 quad_perm:[1,0,3,2] row_mask:0xf bank_mask:0xf
	v_add_f32_dpp v142, v142, v142 quad_perm:[1,0,3,2] row_mask:0xf bank_mask:0xf
	v_pk_mul_f32 v[134:135], v[84:85], v[104:105] op_sel_hi:[1,0]
	ds_read_b128 v[78:81], v112 offset:14080
	ds_read_b128 v[82:85], v112 offset:14096
	ds_read_b32 v104, v108 offset:21376
	s_waitcnt lgkmcnt(10)
	v_pk_fma_f32 v[128:129], v[22:23], v[38:39], v[128:129]
	v_add_f32_dpp v140, v140, v140 quad_perm:[2,3,0,1] row_mask:0xf bank_mask:0xf
	v_add_f32_dpp v142, v142, v142 quad_perm:[2,3,0,1] row_mask:0xf bank_mask:0xf
	v_pk_fma_f32 v[130:131], v[24:25], v[40:41], v[130:131]
	v_pk_fma_f32 v[132:133], v[26:27], v[42:43], v[132:133]
	v_pk_fma_f32 v[134:135], v[28:29], v[44:45], v[134:135]
	ds_read_b128 v[38:41], v112 offset:5888
	ds_read_b128 v[42:45], v112 offset:5904
	s_waitcnt lgkmcnt(10)
	v_pk_fma_f32 v[22:23], v[140:141], v[70:71], v[128:129] op_sel_hi:[0,1,1] neg_lo:[1,0,0] neg_hi:[1,0,0]
	v_pk_fma_f32 v[24:25], v[140:141], v[72:73], v[130:131] op_sel_hi:[0,1,1] neg_lo:[1,0,0] neg_hi:[1,0,0]
	v_pk_fma_f32 v[26:27], v[140:141], v[74:75], v[132:133] op_sel_hi:[0,1,1] neg_lo:[1,0,0] neg_hi:[1,0,0]
	v_pk_fma_f32 v[28:29], v[140:141], v[76:77], v[134:135] op_sel_hi:[0,1,1] neg_lo:[1,0,0] neg_hi:[1,0,0]
	ds_read_b128 v[70:73], v112 offset:9984
	ds_read_b128 v[74:77], v112 offset:10000
	ds_write_b32 v108, v142 offset:25216
	s_waitcnt lgkmcnt(8)
	v_pk_mul_f32 v[136:137], v[22:23], v[30:31]
	v_pk_mul_f32 v[138:139], v[22:23], v[96:97]
	v_pk_fma_f32 v[136:137], v[24:25], v[32:33], v[136:137]
	v_pk_fma_f32 v[138:139], v[24:25], v[98:99], v[138:139]
	v_pk_fma_f32 v[136:137], v[26:27], v[34:35], v[136:137]
	v_pk_fma_f32 v[138:139], v[26:27], v[100:101], v[138:139]
	v_pk_fma_f32 v[136:137], v[28:29], v[36:37], v[136:137]
	v_pk_fma_f32 v[138:139], v[28:29], v[102:103], v[138:139]
	ds_read_b128 v[30:33], v112 offset:2048
	ds_read_b128 v[34:37], v112 offset:2064
	ds_read_b128 v[96:99], v112 offset:18176
	ds_read_b128 v[100:103], v112 offset:18192
	v_add_f32_e32 v140, v136, v137
	v_add_f32_e32 v142, v138, v139
	s_waitcnt lgkmcnt(9)
	v_pk_mul_f32 v[128:129], v[78:79], v[104:105] op_sel_hi:[1,0]
	v_add_f32_dpp v140, v140, v140 row_half_mirror row_mask:0xf bank_mask:0xf
	v_add_f32_dpp v142, v142, v142 row_half_mirror row_mask:0xf bank_mask:0xf
	v_pk_mul_f32 v[130:131], v[80:81], v[104:105] op_sel_hi:[1,0]
	v_pk_mul_f32 v[132:133], v[82:83], v[104:105] op_sel_hi:[1,0]
	v_add_f32_dpp v140, v140, v140 quad_perm:[1,0,3,2] row_mask:0xf bank_mask:0xf
	v_add_f32_dpp v142, v142, v142 quad_perm:[1,0,3,2] row_mask:0xf bank_mask:0xf
	v_pk_mul_f32 v[134:135], v[84:85], v[104:105] op_sel_hi:[1,0]
	ds_read_b128 v[78:81], v112 offset:14336
	ds_read_b128 v[82:85], v112 offset:14352
	ds_read_b32 v104, v108 offset:21504
	s_waitcnt lgkmcnt(10)
	v_pk_fma_f32 v[128:129], v[22:23], v[38:39], v[128:129]
	v_add_f32_dpp v140, v140, v140 quad_perm:[2,3,0,1] row_mask:0xf bank_mask:0xf
	v_add_f32_dpp v142, v142, v142 quad_perm:[2,3,0,1] row_mask:0xf bank_mask:0xf
	v_pk_fma_f32 v[130:131], v[24:25], v[40:41], v[130:131]
	v_pk_fma_f32 v[132:133], v[26:27], v[42:43], v[132:133]
	v_pk_fma_f32 v[134:135], v[28:29], v[44:45], v[134:135]
	ds_read_b128 v[38:41], v112 offset:6144
	ds_read_b128 v[42:45], v112 offset:6160
	s_waitcnt lgkmcnt(10)
	v_pk_fma_f32 v[22:23], v[140:141], v[70:71], v[128:129] op_sel_hi:[0,1,1] neg_lo:[1,0,0] neg_hi:[1,0,0]
	v_pk_fma_f32 v[24:25], v[140:141], v[72:73], v[130:131] op_sel_hi:[0,1,1] neg_lo:[1,0,0] neg_hi:[1,0,0]
	v_pk_fma_f32 v[26:27], v[140:141], v[74:75], v[132:133] op_sel_hi:[0,1,1] neg_lo:[1,0,0] neg_hi:[1,0,0]
	v_pk_fma_f32 v[28:29], v[140:141], v[76:77], v[134:135] op_sel_hi:[0,1,1] neg_lo:[1,0,0] neg_hi:[1,0,0]
	ds_read_b128 v[70:73], v112 offset:10240
	ds_read_b128 v[74:77], v112 offset:10256
	ds_write_b32 v108, v142 offset:25344
	s_waitcnt lgkmcnt(8)
	v_pk_mul_f32 v[136:137], v[22:23], v[30:31]
	v_pk_mul_f32 v[138:139], v[22:23], v[96:97]
	v_pk_fma_f32 v[136:137], v[24:25], v[32:33], v[136:137]
	v_pk_fma_f32 v[138:139], v[24:25], v[98:99], v[138:139]
	v_pk_fma_f32 v[136:137], v[26:27], v[34:35], v[136:137]
	v_pk_fma_f32 v[138:139], v[26:27], v[100:101], v[138:139]
	v_pk_fma_f32 v[136:137], v[28:29], v[36:37], v[136:137]
	v_pk_fma_f32 v[138:139], v[28:29], v[102:103], v[138:139]
	ds_read_b128 v[30:33], v112 offset:2304
	ds_read_b128 v[34:37], v112 offset:2320
	ds_read_b128 v[96:99], v112 offset:18432
	ds_read_b128 v[100:103], v112 offset:18448
	v_add_f32_e32 v140, v136, v137
	v_add_f32_e32 v142, v138, v139
	s_waitcnt lgkmcnt(9)
	v_pk_mul_f32 v[128:129], v[78:79], v[104:105] op_sel_hi:[1,0]
	v_add_f32_dpp v140, v140, v140 row_half_mirror row_mask:0xf bank_mask:0xf
	v_add_f32_dpp v142, v142, v142 row_half_mirror row_mask:0xf bank_mask:0xf
	v_pk_mul_f32 v[130:131], v[80:81], v[104:105] op_sel_hi:[1,0]
	v_pk_mul_f32 v[132:133], v[82:83], v[104:105] op_sel_hi:[1,0]
	v_add_f32_dpp v140, v140, v140 quad_perm:[1,0,3,2] row_mask:0xf bank_mask:0xf
	v_add_f32_dpp v142, v142, v142 quad_perm:[1,0,3,2] row_mask:0xf bank_mask:0xf
	v_pk_mul_f32 v[134:135], v[84:85], v[104:105] op_sel_hi:[1,0]
	ds_read_b128 v[78:81], v112 offset:14592
	ds_read_b128 v[82:85], v112 offset:14608
	ds_read_b32 v104, v108 offset:21632
	s_waitcnt lgkmcnt(10)
	v_pk_fma_f32 v[128:129], v[22:23], v[38:39], v[128:129]
	v_add_f32_dpp v140, v140, v140 quad_perm:[2,3,0,1] row_mask:0xf bank_mask:0xf
	v_add_f32_dpp v142, v142, v142 quad_perm:[2,3,0,1] row_mask:0xf bank_mask:0xf
	v_pk_fma_f32 v[130:131], v[24:25], v[40:41], v[130:131]
	v_pk_fma_f32 v[132:133], v[26:27], v[42:43], v[132:133]
	v_pk_fma_f32 v[134:135], v[28:29], v[44:45], v[134:135]
	ds_read_b128 v[38:41], v112 offset:6400
	ds_read_b128 v[42:45], v112 offset:6416
	s_waitcnt lgkmcnt(10)
	v_pk_fma_f32 v[22:23], v[140:141], v[70:71], v[128:129] op_sel_hi:[0,1,1] neg_lo:[1,0,0] neg_hi:[1,0,0]
	v_pk_fma_f32 v[24:25], v[140:141], v[72:73], v[130:131] op_sel_hi:[0,1,1] neg_lo:[1,0,0] neg_hi:[1,0,0]
	v_pk_fma_f32 v[26:27], v[140:141], v[74:75], v[132:133] op_sel_hi:[0,1,1] neg_lo:[1,0,0] neg_hi:[1,0,0]
	v_pk_fma_f32 v[28:29], v[140:141], v[76:77], v[134:135] op_sel_hi:[0,1,1] neg_lo:[1,0,0] neg_hi:[1,0,0]
	ds_read_b128 v[70:73], v112 offset:10496
	ds_read_b128 v[74:77], v112 offset:10512
	ds_write_b32 v108, v142 offset:25472
	s_waitcnt lgkmcnt(8)
	v_pk_mul_f32 v[136:137], v[22:23], v[30:31]
	v_pk_mul_f32 v[138:139], v[22:23], v[96:97]
	v_pk_fma_f32 v[136:137], v[24:25], v[32:33], v[136:137]
	v_pk_fma_f32 v[138:139], v[24:25], v[98:99], v[138:139]
	v_pk_fma_f32 v[136:137], v[26:27], v[34:35], v[136:137]
	v_pk_fma_f32 v[138:139], v[26:27], v[100:101], v[138:139]
	v_pk_fma_f32 v[136:137], v[28:29], v[36:37], v[136:137]
	v_pk_fma_f32 v[138:139], v[28:29], v[102:103], v[138:139]
	ds_read_b128 v[30:33], v112 offset:2560
	ds_read_b128 v[34:37], v112 offset:2576
	ds_read_b128 v[96:99], v112 offset:18688
	ds_read_b128 v[100:103], v112 offset:18704
	v_add_f32_e32 v140, v136, v137
	v_add_f32_e32 v142, v138, v139
	s_waitcnt lgkmcnt(9)
	v_pk_mul_f32 v[128:129], v[78:79], v[104:105] op_sel_hi:[1,0]
	v_add_f32_dpp v140, v140, v140 row_half_mirror row_mask:0xf bank_mask:0xf
	v_add_f32_dpp v142, v142, v142 row_half_mirror row_mask:0xf bank_mask:0xf
	v_pk_mul_f32 v[130:131], v[80:81], v[104:105] op_sel_hi:[1,0]
	v_pk_mul_f32 v[132:133], v[82:83], v[104:105] op_sel_hi:[1,0]
	v_add_f32_dpp v140, v140, v140 quad_perm:[1,0,3,2] row_mask:0xf bank_mask:0xf
	v_add_f32_dpp v142, v142, v142 quad_perm:[1,0,3,2] row_mask:0xf bank_mask:0xf
	v_pk_mul_f32 v[134:135], v[84:85], v[104:105] op_sel_hi:[1,0]
	ds_read_b128 v[78:81], v112 offset:14848
	ds_read_b128 v[82:85], v112 offset:14864
	ds_read_b32 v104, v108 offset:21760
	s_waitcnt lgkmcnt(10)
	v_pk_fma_f32 v[128:129], v[22:23], v[38:39], v[128:129]
	v_add_f32_dpp v140, v140, v140 quad_perm:[2,3,0,1] row_mask:0xf bank_mask:0xf
	v_add_f32_dpp v142, v142, v142 quad_perm:[2,3,0,1] row_mask:0xf bank_mask:0xf
	v_pk_fma_f32 v[130:131], v[24:25], v[40:41], v[130:131]
	v_pk_fma_f32 v[132:133], v[26:27], v[42:43], v[132:133]
	v_pk_fma_f32 v[134:135], v[28:29], v[44:45], v[134:135]
	ds_read_b128 v[38:41], v112 offset:6656
	ds_read_b128 v[42:45], v112 offset:6672
	s_waitcnt lgkmcnt(10)
	v_pk_fma_f32 v[22:23], v[140:141], v[70:71], v[128:129] op_sel_hi:[0,1,1] neg_lo:[1,0,0] neg_hi:[1,0,0]
	v_pk_fma_f32 v[24:25], v[140:141], v[72:73], v[130:131] op_sel_hi:[0,1,1] neg_lo:[1,0,0] neg_hi:[1,0,0]
	v_pk_fma_f32 v[26:27], v[140:141], v[74:75], v[132:133] op_sel_hi:[0,1,1] neg_lo:[1,0,0] neg_hi:[1,0,0]
	v_pk_fma_f32 v[28:29], v[140:141], v[76:77], v[134:135] op_sel_hi:[0,1,1] neg_lo:[1,0,0] neg_hi:[1,0,0]
	ds_read_b128 v[70:73], v112 offset:10752
	ds_read_b128 v[74:77], v112 offset:10768
	ds_write_b32 v108, v142 offset:25600
	s_waitcnt lgkmcnt(8)
	v_pk_mul_f32 v[136:137], v[22:23], v[30:31]
	v_pk_mul_f32 v[138:139], v[22:23], v[96:97]
	v_pk_fma_f32 v[136:137], v[24:25], v[32:33], v[136:137]
	v_pk_fma_f32 v[138:139], v[24:25], v[98:99], v[138:139]
	v_pk_fma_f32 v[136:137], v[26:27], v[34:35], v[136:137]
	v_pk_fma_f32 v[138:139], v[26:27], v[100:101], v[138:139]
	v_pk_fma_f32 v[136:137], v[28:29], v[36:37], v[136:137]
	v_pk_fma_f32 v[138:139], v[28:29], v[102:103], v[138:139]
	ds_read_b128 v[30:33], v112 offset:2816
	ds_read_b128 v[34:37], v112 offset:2832
	ds_read_b128 v[96:99], v112 offset:18944
	ds_read_b128 v[100:103], v112 offset:18960
	v_add_f32_e32 v140, v136, v137
	v_add_f32_e32 v142, v138, v139
	s_waitcnt lgkmcnt(9)
	v_pk_mul_f32 v[128:129], v[78:79], v[104:105] op_sel_hi:[1,0]
	v_add_f32_dpp v140, v140, v140 row_half_mirror row_mask:0xf bank_mask:0xf
	v_add_f32_dpp v142, v142, v142 row_half_mirror row_mask:0xf bank_mask:0xf
	v_pk_mul_f32 v[130:131], v[80:81], v[104:105] op_sel_hi:[1,0]
	v_pk_mul_f32 v[132:133], v[82:83], v[104:105] op_sel_hi:[1,0]
	v_add_f32_dpp v140, v140, v140 quad_perm:[1,0,3,2] row_mask:0xf bank_mask:0xf
	v_add_f32_dpp v142, v142, v142 quad_perm:[1,0,3,2] row_mask:0xf bank_mask:0xf
	v_pk_mul_f32 v[134:135], v[84:85], v[104:105] op_sel_hi:[1,0]
	ds_read_b128 v[78:81], v112 offset:15104
	ds_read_b128 v[82:85], v112 offset:15120
	ds_read_b32 v104, v108 offset:21888
	s_waitcnt lgkmcnt(10)
	v_pk_fma_f32 v[128:129], v[22:23], v[38:39], v[128:129]
	v_add_f32_dpp v140, v140, v140 quad_perm:[2,3,0,1] row_mask:0xf bank_mask:0xf
	v_add_f32_dpp v142, v142, v142 quad_perm:[2,3,0,1] row_mask:0xf bank_mask:0xf
	v_pk_fma_f32 v[130:131], v[24:25], v[40:41], v[130:131]
	v_pk_fma_f32 v[132:133], v[26:27], v[42:43], v[132:133]
	v_pk_fma_f32 v[134:135], v[28:29], v[44:45], v[134:135]
	ds_read_b128 v[38:41], v112 offset:6912
	ds_read_b128 v[42:45], v112 offset:6928
	s_waitcnt lgkmcnt(10)
	v_pk_fma_f32 v[22:23], v[140:141], v[70:71], v[128:129] op_sel_hi:[0,1,1] neg_lo:[1,0,0] neg_hi:[1,0,0]
	v_pk_fma_f32 v[24:25], v[140:141], v[72:73], v[130:131] op_sel_hi:[0,1,1] neg_lo:[1,0,0] neg_hi:[1,0,0]
	v_pk_fma_f32 v[26:27], v[140:141], v[74:75], v[132:133] op_sel_hi:[0,1,1] neg_lo:[1,0,0] neg_hi:[1,0,0]
	v_pk_fma_f32 v[28:29], v[140:141], v[76:77], v[134:135] op_sel_hi:[0,1,1] neg_lo:[1,0,0] neg_hi:[1,0,0]
	ds_read_b128 v[70:73], v112 offset:11008
	ds_read_b128 v[74:77], v112 offset:11024
	ds_write_b32 v108, v142 offset:25728
	s_waitcnt lgkmcnt(8)
	v_pk_mul_f32 v[136:137], v[22:23], v[30:31]
	v_pk_mul_f32 v[138:139], v[22:23], v[96:97]
	v_pk_fma_f32 v[136:137], v[24:25], v[32:33], v[136:137]
	v_pk_fma_f32 v[138:139], v[24:25], v[98:99], v[138:139]
	v_pk_fma_f32 v[136:137], v[26:27], v[34:35], v[136:137]
	v_pk_fma_f32 v[138:139], v[26:27], v[100:101], v[138:139]
	v_pk_fma_f32 v[136:137], v[28:29], v[36:37], v[136:137]
	v_pk_fma_f32 v[138:139], v[28:29], v[102:103], v[138:139]
	ds_read_b128 v[30:33], v112 offset:3072
	ds_read_b128 v[34:37], v112 offset:3088
	ds_read_b128 v[96:99], v112 offset:19200
	ds_read_b128 v[100:103], v112 offset:19216
	v_add_f32_e32 v140, v136, v137
	v_add_f32_e32 v142, v138, v139
	s_waitcnt lgkmcnt(9)
	v_pk_mul_f32 v[128:129], v[78:79], v[104:105] op_sel_hi:[1,0]
	v_add_f32_dpp v140, v140, v140 row_half_mirror row_mask:0xf bank_mask:0xf
	v_add_f32_dpp v142, v142, v142 row_half_mirror row_mask:0xf bank_mask:0xf
	v_pk_mul_f32 v[130:131], v[80:81], v[104:105] op_sel_hi:[1,0]
	v_pk_mul_f32 v[132:133], v[82:83], v[104:105] op_sel_hi:[1,0]
	v_add_f32_dpp v140, v140, v140 quad_perm:[1,0,3,2] row_mask:0xf bank_mask:0xf
	v_add_f32_dpp v142, v142, v142 quad_perm:[1,0,3,2] row_mask:0xf bank_mask:0xf
	v_pk_mul_f32 v[134:135], v[84:85], v[104:105] op_sel_hi:[1,0]
	ds_read_b128 v[78:81], v112 offset:15360
	ds_read_b128 v[82:85], v112 offset:15376
	ds_read_b32 v104, v108 offset:22016
	s_waitcnt lgkmcnt(10)
	v_pk_fma_f32 v[128:129], v[22:23], v[38:39], v[128:129]
	v_add_f32_dpp v140, v140, v140 quad_perm:[2,3,0,1] row_mask:0xf bank_mask:0xf
	v_add_f32_dpp v142, v142, v142 quad_perm:[2,3,0,1] row_mask:0xf bank_mask:0xf
	v_pk_fma_f32 v[130:131], v[24:25], v[40:41], v[130:131]
	v_pk_fma_f32 v[132:133], v[26:27], v[42:43], v[132:133]
	v_pk_fma_f32 v[134:135], v[28:29], v[44:45], v[134:135]
	ds_read_b128 v[38:41], v112 offset:7168
	ds_read_b128 v[42:45], v112 offset:7184
	s_waitcnt lgkmcnt(10)
	v_pk_fma_f32 v[22:23], v[140:141], v[70:71], v[128:129] op_sel_hi:[0,1,1] neg_lo:[1,0,0] neg_hi:[1,0,0]
	v_pk_fma_f32 v[24:25], v[140:141], v[72:73], v[130:131] op_sel_hi:[0,1,1] neg_lo:[1,0,0] neg_hi:[1,0,0]
	v_pk_fma_f32 v[26:27], v[140:141], v[74:75], v[132:133] op_sel_hi:[0,1,1] neg_lo:[1,0,0] neg_hi:[1,0,0]
	v_pk_fma_f32 v[28:29], v[140:141], v[76:77], v[134:135] op_sel_hi:[0,1,1] neg_lo:[1,0,0] neg_hi:[1,0,0]
	ds_read_b128 v[70:73], v112 offset:11264
	ds_read_b128 v[74:77], v112 offset:11280
	ds_write_b32 v108, v142 offset:25856
	s_waitcnt lgkmcnt(8)
	v_pk_mul_f32 v[136:137], v[22:23], v[30:31]
	v_pk_mul_f32 v[138:139], v[22:23], v[96:97]
	v_pk_fma_f32 v[136:137], v[24:25], v[32:33], v[136:137]
	v_pk_fma_f32 v[138:139], v[24:25], v[98:99], v[138:139]
	v_pk_fma_f32 v[136:137], v[26:27], v[34:35], v[136:137]
	v_pk_fma_f32 v[138:139], v[26:27], v[100:101], v[138:139]
	v_pk_fma_f32 v[136:137], v[28:29], v[36:37], v[136:137]
	v_pk_fma_f32 v[138:139], v[28:29], v[102:103], v[138:139]
	ds_read_b128 v[30:33], v112 offset:3328
	ds_read_b128 v[34:37], v112 offset:3344
	ds_read_b128 v[96:99], v112 offset:19456
	ds_read_b128 v[100:103], v112 offset:19472
	v_add_f32_e32 v140, v136, v137
	v_add_f32_e32 v142, v138, v139
	s_waitcnt lgkmcnt(9)
	v_pk_mul_f32 v[128:129], v[78:79], v[104:105] op_sel_hi:[1,0]
	v_add_f32_dpp v140, v140, v140 row_half_mirror row_mask:0xf bank_mask:0xf
	v_add_f32_dpp v142, v142, v142 row_half_mirror row_mask:0xf bank_mask:0xf
	v_pk_mul_f32 v[130:131], v[80:81], v[104:105] op_sel_hi:[1,0]
	v_pk_mul_f32 v[132:133], v[82:83], v[104:105] op_sel_hi:[1,0]
	v_add_f32_dpp v140, v140, v140 quad_perm:[1,0,3,2] row_mask:0xf bank_mask:0xf
	v_add_f32_dpp v142, v142, v142 quad_perm:[1,0,3,2] row_mask:0xf bank_mask:0xf
	v_pk_mul_f32 v[134:135], v[84:85], v[104:105] op_sel_hi:[1,0]
	ds_read_b128 v[78:81], v112 offset:15616
	ds_read_b128 v[82:85], v112 offset:15632
	ds_read_b32 v104, v108 offset:22144
	s_waitcnt lgkmcnt(10)
	v_pk_fma_f32 v[128:129], v[22:23], v[38:39], v[128:129]
	v_add_f32_dpp v140, v140, v140 quad_perm:[2,3,0,1] row_mask:0xf bank_mask:0xf
	v_add_f32_dpp v142, v142, v142 quad_perm:[2,3,0,1] row_mask:0xf bank_mask:0xf
	v_pk_fma_f32 v[130:131], v[24:25], v[40:41], v[130:131]
	v_pk_fma_f32 v[132:133], v[26:27], v[42:43], v[132:133]
	v_pk_fma_f32 v[134:135], v[28:29], v[44:45], v[134:135]
	ds_read_b128 v[38:41], v112 offset:7424
	ds_read_b128 v[42:45], v112 offset:7440
	s_waitcnt lgkmcnt(10)
	v_pk_fma_f32 v[22:23], v[140:141], v[70:71], v[128:129] op_sel_hi:[0,1,1] neg_lo:[1,0,0] neg_hi:[1,0,0]
	v_pk_fma_f32 v[24:25], v[140:141], v[72:73], v[130:131] op_sel_hi:[0,1,1] neg_lo:[1,0,0] neg_hi:[1,0,0]
	v_pk_fma_f32 v[26:27], v[140:141], v[74:75], v[132:133] op_sel_hi:[0,1,1] neg_lo:[1,0,0] neg_hi:[1,0,0]
	v_pk_fma_f32 v[28:29], v[140:141], v[76:77], v[134:135] op_sel_hi:[0,1,1] neg_lo:[1,0,0] neg_hi:[1,0,0]
	ds_read_b128 v[70:73], v112 offset:11520
	ds_read_b128 v[74:77], v112 offset:11536
	ds_write_b32 v108, v142 offset:25984
	s_waitcnt lgkmcnt(8)
	v_pk_mul_f32 v[136:137], v[22:23], v[30:31]
	v_pk_mul_f32 v[138:139], v[22:23], v[96:97]
	v_pk_fma_f32 v[136:137], v[24:25], v[32:33], v[136:137]
	v_pk_fma_f32 v[138:139], v[24:25], v[98:99], v[138:139]
	v_pk_fma_f32 v[136:137], v[26:27], v[34:35], v[136:137]
	v_pk_fma_f32 v[138:139], v[26:27], v[100:101], v[138:139]
	v_pk_fma_f32 v[136:137], v[28:29], v[36:37], v[136:137]
	v_pk_fma_f32 v[138:139], v[28:29], v[102:103], v[138:139]
	ds_read_b128 v[30:33], v112 offset:3584
	ds_read_b128 v[34:37], v112 offset:3600
	ds_read_b128 v[96:99], v112 offset:19712
	ds_read_b128 v[100:103], v112 offset:19728
	v_add_f32_e32 v140, v136, v137
	v_add_f32_e32 v142, v138, v139
	s_waitcnt lgkmcnt(9)
	v_pk_mul_f32 v[128:129], v[78:79], v[104:105] op_sel_hi:[1,0]
	v_add_f32_dpp v140, v140, v140 row_half_mirror row_mask:0xf bank_mask:0xf
	v_add_f32_dpp v142, v142, v142 row_half_mirror row_mask:0xf bank_mask:0xf
	v_pk_mul_f32 v[130:131], v[80:81], v[104:105] op_sel_hi:[1,0]
	v_pk_mul_f32 v[132:133], v[82:83], v[104:105] op_sel_hi:[1,0]
	v_add_f32_dpp v140, v140, v140 quad_perm:[1,0,3,2] row_mask:0xf bank_mask:0xf
	v_add_f32_dpp v142, v142, v142 quad_perm:[1,0,3,2] row_mask:0xf bank_mask:0xf
	v_pk_mul_f32 v[134:135], v[84:85], v[104:105] op_sel_hi:[1,0]
	ds_read_b128 v[78:81], v112 offset:15872
	ds_read_b128 v[82:85], v112 offset:15888
	ds_read_b32 v104, v108 offset:22272
	s_waitcnt lgkmcnt(10)
	v_pk_fma_f32 v[128:129], v[22:23], v[38:39], v[128:129]
	v_add_f32_dpp v140, v140, v140 quad_perm:[2,3,0,1] row_mask:0xf bank_mask:0xf
	v_add_f32_dpp v142, v142, v142 quad_perm:[2,3,0,1] row_mask:0xf bank_mask:0xf
	v_pk_fma_f32 v[130:131], v[24:25], v[40:41], v[130:131]
	v_pk_fma_f32 v[132:133], v[26:27], v[42:43], v[132:133]
	v_pk_fma_f32 v[134:135], v[28:29], v[44:45], v[134:135]
	ds_read_b128 v[38:41], v112 offset:7680
	ds_read_b128 v[42:45], v112 offset:7696
	s_waitcnt lgkmcnt(10)
	v_pk_fma_f32 v[22:23], v[140:141], v[70:71], v[128:129] op_sel_hi:[0,1,1] neg_lo:[1,0,0] neg_hi:[1,0,0]
	v_pk_fma_f32 v[24:25], v[140:141], v[72:73], v[130:131] op_sel_hi:[0,1,1] neg_lo:[1,0,0] neg_hi:[1,0,0]
	v_pk_fma_f32 v[26:27], v[140:141], v[74:75], v[132:133] op_sel_hi:[0,1,1] neg_lo:[1,0,0] neg_hi:[1,0,0]
	v_pk_fma_f32 v[28:29], v[140:141], v[76:77], v[134:135] op_sel_hi:[0,1,1] neg_lo:[1,0,0] neg_hi:[1,0,0]
	ds_read_b128 v[70:73], v112 offset:11776
	ds_read_b128 v[74:77], v112 offset:11792
	ds_write_b32 v108, v142 offset:26112
	s_waitcnt lgkmcnt(8)
	v_pk_mul_f32 v[136:137], v[22:23], v[30:31]
	v_pk_mul_f32 v[138:139], v[22:23], v[96:97]
	v_pk_fma_f32 v[136:137], v[24:25], v[32:33], v[136:137]
	v_pk_fma_f32 v[138:139], v[24:25], v[98:99], v[138:139]
	v_pk_fma_f32 v[136:137], v[26:27], v[34:35], v[136:137]
	v_pk_fma_f32 v[138:139], v[26:27], v[100:101], v[138:139]
	v_pk_fma_f32 v[136:137], v[28:29], v[36:37], v[136:137]
	v_pk_fma_f32 v[138:139], v[28:29], v[102:103], v[138:139]
	ds_read_b128 v[30:33], v112 offset:3840
	ds_read_b128 v[34:37], v112 offset:3856
	ds_read_b128 v[96:99], v112 offset:19968
	ds_read_b128 v[100:103], v112 offset:19984
	v_add_f32_e32 v140, v136, v137
	v_add_f32_e32 v142, v138, v139
	s_waitcnt lgkmcnt(9)
	v_pk_mul_f32 v[128:129], v[78:79], v[104:105] op_sel_hi:[1,0]
	v_add_f32_dpp v140, v140, v140 row_half_mirror row_mask:0xf bank_mask:0xf
	v_add_f32_dpp v142, v142, v142 row_half_mirror row_mask:0xf bank_mask:0xf
	v_pk_mul_f32 v[130:131], v[80:81], v[104:105] op_sel_hi:[1,0]
	v_pk_mul_f32 v[132:133], v[82:83], v[104:105] op_sel_hi:[1,0]
	v_add_f32_dpp v140, v140, v140 quad_perm:[1,0,3,2] row_mask:0xf bank_mask:0xf
	v_add_f32_dpp v142, v142, v142 quad_perm:[1,0,3,2] row_mask:0xf bank_mask:0xf
	v_pk_mul_f32 v[134:135], v[84:85], v[104:105] op_sel_hi:[1,0]
	ds_read_b128 v[78:81], v112 offset:16128
	ds_read_b128 v[82:85], v112 offset:16144
	ds_read_b32 v104, v108 offset:22400
	s_waitcnt lgkmcnt(10)
	v_pk_fma_f32 v[128:129], v[22:23], v[38:39], v[128:129]
	v_add_f32_dpp v140, v140, v140 quad_perm:[2,3,0,1] row_mask:0xf bank_mask:0xf
	v_add_f32_dpp v142, v142, v142 quad_perm:[2,3,0,1] row_mask:0xf bank_mask:0xf
	v_pk_fma_f32 v[130:131], v[24:25], v[40:41], v[130:131]
	v_pk_fma_f32 v[132:133], v[26:27], v[42:43], v[132:133]
	v_pk_fma_f32 v[134:135], v[28:29], v[44:45], v[134:135]
	ds_read_b128 v[38:41], v112 offset:7936
	ds_read_b128 v[42:45], v112 offset:7952
	s_waitcnt lgkmcnt(10)
	v_pk_fma_f32 v[22:23], v[140:141], v[70:71], v[128:129] op_sel_hi:[0,1,1] neg_lo:[1,0,0] neg_hi:[1,0,0]
	v_pk_fma_f32 v[24:25], v[140:141], v[72:73], v[130:131] op_sel_hi:[0,1,1] neg_lo:[1,0,0] neg_hi:[1,0,0]
	v_pk_fma_f32 v[26:27], v[140:141], v[74:75], v[132:133] op_sel_hi:[0,1,1] neg_lo:[1,0,0] neg_hi:[1,0,0]
	v_pk_fma_f32 v[28:29], v[140:141], v[76:77], v[134:135] op_sel_hi:[0,1,1] neg_lo:[1,0,0] neg_hi:[1,0,0]
	ds_read_b128 v[70:73], v112 offset:12032
	ds_read_b128 v[74:77], v112 offset:12048
	ds_write_b32 v108, v142 offset:26240
	s_waitcnt lgkmcnt(8)
	v_pk_mul_f32 v[136:137], v[22:23], v[30:31]
	v_pk_mul_f32 v[138:139], v[22:23], v[96:97]
	v_pk_fma_f32 v[136:137], v[24:25], v[32:33], v[136:137]
	v_pk_fma_f32 v[138:139], v[24:25], v[98:99], v[138:139]
	v_pk_fma_f32 v[136:137], v[26:27], v[34:35], v[136:137]
	v_pk_fma_f32 v[138:139], v[26:27], v[100:101], v[138:139]
	v_pk_fma_f32 v[136:137], v[28:29], v[36:37], v[136:137]
	v_pk_fma_f32 v[138:139], v[28:29], v[102:103], v[138:139]
	ds_read_b128 v[96:99], v112 offset:20224
	ds_read_b128 v[100:103], v112 offset:20240
	v_add_f32_e32 v140, v136, v137
	v_add_f32_e32 v142, v138, v139
	s_waitcnt lgkmcnt(7)
	v_pk_mul_f32 v[128:129], v[78:79], v[104:105] op_sel_hi:[1,0]
	v_add_f32_dpp v140, v140, v140 row_half_mirror row_mask:0xf bank_mask:0xf
	v_add_f32_dpp v142, v142, v142 row_half_mirror row_mask:0xf bank_mask:0xf
	v_pk_mul_f32 v[130:131], v[80:81], v[104:105] op_sel_hi:[1,0]
	v_pk_mul_f32 v[132:133], v[82:83], v[104:105] op_sel_hi:[1,0]
	v_add_f32_dpp v140, v140, v140 quad_perm:[1,0,3,2] row_mask:0xf bank_mask:0xf
	v_add_f32_dpp v142, v142, v142 quad_perm:[1,0,3,2] row_mask:0xf bank_mask:0xf
	v_pk_mul_f32 v[134:135], v[84:85], v[104:105] op_sel_hi:[1,0]
	s_waitcnt lgkmcnt(5)
	v_pk_fma_f32 v[128:129], v[22:23], v[38:39], v[128:129]
	v_add_f32_dpp v140, v140, v140 quad_perm:[2,3,0,1] row_mask:0xf bank_mask:0xf
	v_add_f32_dpp v142, v142, v142 quad_perm:[2,3,0,1] row_mask:0xf bank_mask:0xf
	v_pk_fma_f32 v[130:131], v[24:25], v[40:41], v[130:131]
	v_pk_fma_f32 v[132:133], v[26:27], v[42:43], v[132:133]
	v_pk_fma_f32 v[134:135], v[28:29], v[44:45], v[134:135]
	s_waitcnt lgkmcnt(3)
	v_pk_fma_f32 v[22:23], v[140:141], v[70:71], v[128:129] op_sel_hi:[0,1,1] neg_lo:[1,0,0] neg_hi:[1,0,0]
	v_pk_fma_f32 v[24:25], v[140:141], v[72:73], v[130:131] op_sel_hi:[0,1,1] neg_lo:[1,0,0] neg_hi:[1,0,0]
	v_pk_fma_f32 v[26:27], v[140:141], v[74:75], v[132:133] op_sel_hi:[0,1,1] neg_lo:[1,0,0] neg_hi:[1,0,0]
	v_pk_fma_f32 v[28:29], v[140:141], v[76:77], v[134:135] op_sel_hi:[0,1,1] neg_lo:[1,0,0] neg_hi:[1,0,0]
	ds_write_b32 v108, v142 offset:26368
	s_waitcnt lgkmcnt(1)
	v_pk_mul_f32 v[138:139], v[22:23], v[96:97]
	v_pk_fma_f32 v[138:139], v[24:25], v[98:99], v[138:139]
	v_pk_fma_f32 v[138:139], v[26:27], v[100:101], v[138:139]
	v_pk_fma_f32 v[138:139], v[28:29], v[102:103], v[138:139]
	v_add_f32_e32 v142, v138, v139
	s_nop 1
	v_add_f32_dpp v142, v142, v142 row_half_mirror row_mask:0xf bank_mask:0xf
	s_nop 1
	v_add_f32_dpp v142, v142, v142 quad_perm:[1,0,3,2] row_mask:0xf bank_mask:0xf
	s_nop 1
	v_add_f32_dpp v142, v142, v142 quad_perm:[2,3,0,1] row_mask:0xf bank_mask:0xf
	ds_write_b32 v108, v142 offset:26496
	s_add_u32 s28, s28, 16
	s_cmp_lt_u32 s28, s25
	s_cbranch_scc1 .Lrw0_loop
	s_waitcnt lgkmcnt(0)
	s_barrier
	ds_read_b32 v89, v5 offset:24576
	ds_read_b32 v90, v5 offset:24640
	s_sub_u32 s98, s28, 16
	v_add_u32_e32 v87, s98, v127
	v_mad_i64_i32 v[104:105], vcc, v87, v20, v[18:19]
	s_waitcnt lgkmcnt(0)
	v_cvt_pk_bf16_f32 v89, v89, v90
	global_store_short v[104:105], v89, off
	global_store_short_d16_hi v[104:105], v89, off offset:32
	v_lshrrev_b32_e32 v87, 2, v108
	v_lshl_add_u32 v87, s17, 4, v87
	v_lshl_add_u32 v89, v87, 8, v112
	s_cmp_eq_u32 s18, 3
	s_cbranch_scc0 .Lrw0_f_not3
	s_load_dwordx2 s[36:37], s[14:15], 0x120
	s_waitcnt lgkmcnt(0)
	s_lshl_b32 s98, s42, 14
	s_add_u32 s36, s36, s98
	s_addc_u32 s37, s37, 0
	s_add_u32 s36, s36, 0x5e00000
	s_addc_u32 s37, s37, 0
	global_store_dwordx4 v89, v[22:25], s[36:37]
	global_store_dwordx4 v89, v[26:29], s[36:37] offset:16
	s_branch .Lrw0_f_done
.Lrw0_f_not3:
	s_cmp_eq_u32 s18, 0
	s_cbranch_scc0 .Lrw0_f_done
	s_load_dwordx2 s[36:37], s[14:15], 0x148
	s_waitcnt lgkmcnt(0)
	s_lshl_b32 s98, s16, 14
	s_add_u32 s36, s36, s98
	s_addc_u32 s37, s37, 0
	global_store_dwordx4 v89, v[22:25], s[36:37]
	global_store_dwordx4 v89, v[26:29], s[36:37] offset:16

.LBB0_2227:
	s_or_b64 exec, exec, s[0:1]
	s_mov_b32 s0, s76
	s_mov_b32 s1, s74
	s_waitcnt lgkmcnt(0)
	s_barrier
	s_mov_b32 s85, 0
	v_readlane_b32 s0, v241, 1
	v_readlane_b32 s6, v241, 7
	v_readlane_b32 s1, v241, 2
	v_readlane_b32 s7, v241, 8
	s_add_u32 s0, s6, 0xb00000
	s_addc_u32 s1, s7, 0
	v_readlane_b32 s4, v241, 5
	v_writelane_b32 v240, s0, 56
	v_readlane_b32 s5, v241, 6
	v_readlane_b32 s2, v241, 3
	v_writelane_b32 v240, s1, 57
	s_add_u32 s0, s4, 0x1600000
	s_addc_u32 s1, s5, 0
	v_readlane_b32 s3, v241, 4
	v_readlane_b32 s8, v241, 9
	v_readlane_b32 s9, v241, 10
	v_readlane_b32 s10, v241, 11
	v_readlane_b32 s11, v241, 12
	v_readlane_b32 s12, v241, 13
	v_readlane_b32 s13, v241, 14
	v_readlane_b32 s14, v241, 15
	v_readlane_b32 s15, v241, 16
	v_writelane_b32 v240, s0, 58
	v_bfrev_b32_e32 v1, 0.5
	v_mov_b32_e32 v0, 0
	v_writelane_b32 v240, s1, 59
	v_readlane_b32 s0, v241, 41
	v_readlane_b32 s6, v241, 47
	v_readlane_b32 s1, v241, 42
	v_readlane_b32 s7, v241, 48
	s_add_u32 s0, s6, 0x400000
	v_readlane_b32 s3, v241, 44
	s_addc_u32 s1, s7, 0
	v_writelane_b32 v240, s0, 50
	v_mov_b32_e32 v109, 0x12010
	s_movk_i32 s60, 0x104
	s_movk_i32 s78, 0x7fff
	s_movk_i32 s61, 0x1600
	s_movk_i32 s62, 0x5800
	s_mov_b32 s79, 0x2aaaaaab
	s_movk_i32 s86, 0x1520
	s_mov_b32 s87, 0xffff0000
	s_mov_b32 s3, 0x7060302
	s_movk_i32 s63, 0x90
	s_movk_i32 s70, 0x81
	s_movk_i32 s64, 0x480
	s_movk_i32 s65, 0xff40
	s_movk_i32 s66, 0x3c0
	s_movk_i32 s67, 0x280
	s_movk_i32 s71, 0xffe8
	v_mov_b32_e32 v111, 0x3ecc95a3
	s_movk_i32 s72, 0xa00
	s_movk_i32 s73, 0x2b0
	v_mov_b32_e32 v116, 1
	v_mov_b32_e32 v117, 0x160000
	v_mov_b32_e32 v86, 1.0
	v_mov_b32_e32 v118, 0xf149f2ca
	v_mov_b32_e32 v119, 0xb700
	v_mov_b32_e32 v120, 0x280
	v_mov_b32_e32 v121, 0xffffff00
	v_mov_b32_e32 v122, 0x2380
	v_mov_b32_e32 v88, 0x3f317218
	v_mov_b32_e32 v123, 0x7f800000
	v_mov_b32_e32 v124, 0x7fc00000
	v_mov_b32_e32 v125, 0xff800000
	v_lshl_or_b32 v126, v227, 2, v1
	v_mov_b32_e32 v127, 0x100
	s_mov_b32 s74, 0x800000
	v_readlane_b32 s2, v241, 43
	v_readlane_b32 s4, v241, 45
	v_readlane_b32 s5, v241, 46
	v_readlane_b32 s8, v241, 49
	v_readlane_b32 s9, v241, 50
	v_readlane_b32 s10, v241, 51
	v_readlane_b32 s11, v241, 52
	v_readlane_b32 s12, v241, 53
	v_readlane_b32 s13, v241, 54
	v_readlane_b32 s14, v241, 55
	v_readlane_b32 s15, v241, 56
	v_writelane_b32 v240, s1, 51
	s_getreg_b32 s98, hwreg(HW_REG_LDS_ALLOC, 0, 12)
	v_readlane_b32 s100, v241, 15
	v_readlane_b32 s101, v241, 16
	s_cmp_lg_u32 s98, 0
	s_cselect_b32 s98, 1, 0
	s_nop 2
	s_load_dword s99, s[100:101], 0x10
	s_waitcnt lgkmcnt(0)
	s_sub_u32 s99, s99, 224
	s_cmp_le_u32 s99, 64
	s_cselect_b32 s98, s98, 0
	s_nop 0
	v_writelane_b32 v246, s98, 5
	s_branch .LBB0_2230

.LBB0_2230:
	v_mov_b32_e32 v1, v226
	s_nop 0
	v_cmp_eq_u32_e32 vcc, 0, v1
	s_and_saveexec_b64 s[0:1], vcc
	s_cbranch_execz .LBB0_2234
	s_mov_b64 s[6:7], exec
	v_mbcnt_lo_u32_b32 v1, s6, 0
	v_mbcnt_hi_u32_b32 v1, s7, v1
	v_cmp_eq_u32_e32 vcc, 0, v1
	s_and_saveexec_b64 s[4:5], vcc
	s_cbranch_execz .LBB0_2233
	s_bcnt1_i32_b64 s2, s[6:7]
	v_readlane_b32 s8, v241, 1
	v_mov_b32_e32 v2, s2
	v_readlane_b32 s22, v241, 15
	v_readlane_b32 s23, v241, 16
	v_readlane_b32 s9, v241, 2
	v_readlane_b32 s10, v241, 3
	v_readlane_b32 s11, v241, 4
	v_readlane_b32 s12, v241, 5
	v_readlane_b32 s13, v241, 6
	v_readlane_b32 s98, v246, 5
	s_nop 3
	s_bitcmp1_b32 s98, 0
	s_cbranch_scc1 .Lq1_B
.Lq1_A:
	v_mov_b32_e32 v242, 1
	global_atomic_add v242, v0, v242, s[22:23] offset:4 sc0
	s_waitcnt vmcnt(0)
	v_readfirstlane_b32 s99, v242
	s_nop 3
	s_cmp_lt_u32 s99, 240
	s_cbranch_scc1 .Lq1_mapA
	s_cmp_eq_u32 s98, 2
	s_cbranch_scc1 .Lq1_none
	s_mov_b32 s98, 3
	s_nop 0
	v_writelane_b32 v246, s98, 5
.Lq1_B:
	v_mov_b32_e32 v242, 1
	global_atomic_add v242, v0, v242, s[22:23] offset:12 sc0
	s_waitcnt vmcnt(0)
	v_readfirstlane_b32 s99, v242
	s_nop 3
	s_cmp_lt_u32 s99, 0x1280
	s_cbranch_scc1 .Lq1_mapB
	s_cmp_eq_u32 s98, 3
	s_cbranch_scc1 .Lq1_none
	s_mov_b32 s98, 2
	s_nop 0
	v_writelane_b32 v246, s98, 5
	s_branch .Lq1_A

.Lrw1_gdone:
	s_sub_u32 s29, s23, 1
	s_lshr_b32 s30, s23, 1
	s_cmp_eq_u32 s18, 0
	s_cselect_b32 s25, s30, s23
	s_sub_u32 s31, s18, 1
	s_cmp_lt_u32 s31, 2
	s_cselect_b32 s24, s30, 0
	s_cmp_eq_u32 s18, 2
	s_cselect_b32 s40, 0, 1.0
	s_mov_b32 s41, s40
	s_lshl_b32 s42, s21, 1
	s_add_u32 s42, s42, 1
	s_lshl_b32 s42, s42, 1
	s_add_u32 s42, s42, s20
	s_lshl_b32 s42, s42, 2
	s_add_u32 s42, s42, s19
	v_readlane_b32 s14, v246, 10
	v_readlane_b32 s15, v246, 11
	s_nop 4
	s_load_dwordx2 s[4:5], s[14:15], 0x178
	s_load_dwordx2 s[6:7], s[14:15], 0x188
	s_load_dwordx2 s[8:9], s[14:15], 0x198
	s_load_dwordx2 s[10:11], s[14:15], 0x98
	s_load_dwordx2 s[12:13], s[14:15], 0xc8
	s_load_dwordx2 s[26:27], s[14:15], 0xd0
	v_and_b32_e32 v87, 15, v226
	v_lshrrev_b32_e32 v127, 4, v226
	v_lshlrev_b32_e32 v95, 4, v87
	v_lshrrev_b32_e32 v108, 3, v226
	v_lshlrev_b32_e32 v108, 2, v108
	v_and_b32_e32 v112, 7, v226
	v_lshlrev_b32_e32 v112, 5, v112
	v_mul_u32_u24_e32 v93, 80, v87
	v_lshlrev_b32_e32 v110, 4, v226
	v_lshlrev_b32_e32 v115, 2, v226
	v_mul_u32_u24_e32 v1, 0x180, v127
	v_lshl_add_u32 v1, v87, 3, v1
	v_lshlrev_b32_e32 v2, 8, v127
	v_add_u32_e32 v3, v2, v95
	v_lshl_add_u32 v2, v87, 3, v2
	v_lshrrev_b32_e32 v89, 3, v87
	v_and_b32_e32 v90, 7, v87
	v_lshlrev_b32_e32 v91, 7, v127
	v_lshl_add_u32 v91, v90, 4, v91
	s_lshr_b32 s98, s17, 1
	v_add_u32_e32 v91, 0x5000, v91
	v_add_u32_e32 v92, 0xa000, v110
	v_cmp_eq_u32_e32 vcc, s98, v89
	s_nop 1
	v_cndmask_b32_e32 v4, v92, v91, vcc
	v_lshlrev_b32_e32 v5, 7, v127
	v_lshl_add_u32 v5, v87, 2, v5
	s_mov_b32 s30, 0xaaaaaab
	s_lshl_b32 s31, s19, 7
	v_mul_hi_u32 v87, v226, s30
	v_mul_u32_u24_e32 v89, 24, v87
	v_sub_u32_e32 v89, v226, v89
	v_add_u32_e32 v15, -1, v87
	v_lshrrev_b32_e32 v90, 3, v89
	v_and_b32_e32 v89, 7, v89
	v_lshlrev_b32_e32 v90, 9, v90
	v_lshl_add_u32 v91, v89, 4, v90
	v_add_u32_e32 v91, s31, v91
	v_add_u32_e32 v91, 0xd20, v91
	s_add_u32 s34, s22, s29
	s_cmp_eq_u32 s20, 0
	s_cselect_b32 s34, s22, s34
	s_waitcnt lgkmcnt(0)
	s_mul_i32 s98, s34, 0x1520
	s_mul_hi_u32 s99, s34, 0x1520
	s_add_u32 s100, s4, s98
	s_addc_u32 s101, s5, s99
	s_mul_i32 s98, s34, 0xa00
	s_mul_hi_u32 s99, s34, 0xa00
	s_add_u32 s98, s6, s98
	s_addc_u32 s99, s7, s99
	v_mov_b32_e32 v92, 0
	v_mov_b32_e32 v6, s100
	v_mov_b32_e32 v7, s101
	v_add_co_u32_e32 v6, vcc, v6, v91
	s_nop 1
	v_addc_co_u32_e32 v7, vcc, 0, v7, vcc
	s_movk_i32 s36, 0x1520
	s_mul_i32 s37, s36, -1
	s_cmp_eq_u32 s20, 0
	s_cselect_b32 s34, s36, s37
	s_movk_i32 s36, 0xa00
	s_mul_i32 s37, s36, -1
	s_cselect_b32 s35, s36, s37
	v_mov_b32_e32 v12, s34
	v_add_u32_e32 v92, 0x100, v226
	v_mul_hi_u32 v87, v92, s30
	v_mul_u32_u24_e32 v89, 24, v87
	v_sub_u32_e32 v89, v92, v89
	v_add_u32_e32 v16, -1, v87
	v_lshrrev_b32_e32 v90, 3, v89
	v_and_b32_e32 v89, 7, v89
	v_lshlrev_b32_e32 v90, 9, v90
	v_lshl_add_u32 v91, v89, 4, v90
	v_add_u32_e32 v91, s31, v91
	v_add_u32_e32 v91, 0xd20, v91
	s_lshl_b32 s36, s20, 9
	s_add_u32 s36, s36, s31
	v_add_u32_e32 v92, 0xffffff50, v226
	v_lshrrev_b32_e32 v21, 4, v92
	v_and_b32_e32 v87, 15, v92
	v_lshrrev_b32_e32 v89, 3, v87
	v_and_b32_e32 v87, 7, v87
	v_lshlrev_b32_e32 v89, 10, v89
	v_lshl_add_u32 v90, v87, 4, v89
	v_add_u32_e32 v90, s36, v90
	v_cmp_gt_u32_e32 vcc, 0xb0, v226
	s_nop 1
	v_cndmask_b32_e32 v16, v21, v16, vcc
	v_cndmask_b32_e32 v91, v90, v91, vcc
	v_mov_b32_e32 v87, s35
	v_mov_b32_e32 v89, s34
	v_cndmask_b32_e32 v13, v87, v89, vcc
	v_mov_b32_e32 v87, s98
	v_mov_b32_e32 v89, s100
	v_cndmask_b32_e32 v8, v87, v89, vcc
	v_mov_b32_e32 v87, s99
	v_mov_b32_e32 v89, s101
	v_cndmask_b32_e32 v9, v87, v89, vcc
	v_add_co_u32_e32 v8, vcc, v8, v91
	s_nop 1
	v_addc_co_u32_e32 v9, vcc, 0, v9, vcc
	v_add_u32_e32 v92, 0x50, v226
	v_lshrrev_b32_e32 v17, 4, v92
	v_and_b32_e32 v87, 15, v92
	v_lshrrev_b32_e32 v89, 3, v87
	v_and_b32_e32 v87, 7, v87
	v_lshlrev_b32_e32 v89, 10, v89
	v_lshl_add_u32 v91, v87, 4, v89
	v_add_u32_e32 v91, s36, v91
	v_mov_b32_e32 v10, s98
	v_mov_b32_e32 v11, s99
	v_add_co_u32_e32 v10, vcc, v10, v91
	s_nop 1
	v_addc_co_u32_e32 v11, vcc, 0, v11, vcc
	v_mov_b32_e32 v14, s35
	s_add_u32 s30, s22, s29
	s_cmp_eq_u32 s20, 0
	s_cselect_b32 s30, s22, s30
	s_lshl_b32 s36, s19, 7
	s_lshl_b32 s37, s17, 5
	s_add_u32 s36, s36, s37
	s_cmp_eq_u32 s18, 2
	s_cbranch_scc1 .Lrw1_o_u2
	s_lshl_b32 s37, s20, 9
	s_add_u32 s36, s36, s37
	s_mul_i32 s98, s30, 0xa00
	s_mul_hi_u32 s99, s30, 0xa00
	s_add_u32 s98, s98, s36
	s_addc_u32 s99, s99, 0
	s_add_u32 s98, s8, s98
	s_addc_u32 s99, s9, s99
	s_movk_i32 s36, 0xa00
	s_mul_i32 s37, s36, -1
	s_cmp_eq_u32 s20, 0
	s_cselect_b32 s35, s36, s37
	s_branch .Lrw1_o_done

.Lrw1_o_done:
	v_and_b32_e32 v87, 15, v226
	v_lshlrev_b32_e32 v87, 1, v87
	v_mov_b32_e32 v18, s98
	v_mov_b32_e32 v19, s99
	v_add_co_u32_e32 v18, vcc, v18, v87
	s_nop 1
	v_addc_co_u32_e32 v19, vcc, 0, v19, vcc
	v_mov_b32_e32 v20, s35
	s_lshl_b32 s36, s19, 8
	s_add_u32 s98, s10, s36
	s_addc_u32 s99, s11, 0
	s_add_u32 s98, s98, 0x1000
	s_addc_u32 s99, s99, 0
	global_load_dwordx4 v[70:73], v95, s[98:99]
	global_load_dwordx4 v[74:77], v95, s[98:99] offset:1024
	global_load_dwordx4 v[78:81], v95, s[98:99] offset:2048
	s_add_u32 s98, s12, s36
	s_addc_u32 s99, s13, 0
	s_add_u32 s100, s26, s36
	s_addc_u32 s101, s27, 0
	global_load_dwordx4 v[82:85], v95, s[98:99] offset:1024
	global_load_dwordx4 v[96:99], v95, s[100:101] offset:1024
	v_lshrrev_b32_e32 v90, 4, v95
	v_mul_u32_u24_e32 v21, 80, v90
	s_waitcnt vmcnt(0)
	ds_write_b128 v21, v[70:73] offset:46080
	ds_write_b128 v21, v[74:77] offset:46096
	ds_write_b128 v21, v[78:81] offset:46112
	ds_write_b128 v21, v[82:85] offset:46128
	ds_write_b128 v21, v[96:99] offset:46144
	v_lshrrev_b32_e32 v87, 2, v108
	v_lshl_add_u32 v87, s17, 4, v87
	v_lshl_add_u32 v89, v87, 8, v112
	v_mov_b32_e32 v22, 0
	v_mov_b32_e32 v23, 0
	v_mov_b32_e32 v24, 0
	v_mov_b32_e32 v25, 0
	v_mov_b32_e32 v26, 0
	v_mov_b32_e32 v27, 0
	v_mov_b32_e32 v28, 0
	v_mov_b32_e32 v29, 0
	s_cmp_eq_u32 s18, 0
	s_cbranch_scc0 .Lrw1_s_not0
	s_load_dwordx2 s[36:37], s[14:15], 0x28
	s_waitcnt lgkmcnt(0)
	s_lshl_b32 s98, s42, 14
	s_add_u32 s36, s36, s98
	s_addc_u32 s37, s37, 0
	global_load_dwordx4 v[22:25], v89, s[36:37]
	global_load_dwordx4 v[26:29], v89, s[36:37] offset:16
	s_branch .Lrw1_s_done
